# phase4 FFT stage-B GEMM rewritten: 8 waves on the 64 useful rows, DFT fragments in registers, 4-slot LDS-DMA ring, LDS-reduced row sums
# speedup vs baseline: 1.0144x; 1.0021x over previous
.LBB0_611:
	s_cmpk_lg_u32 s84, 0x100
	s_cbranch_scc1 .Lfftb_orig
	v_lshrrev_b32_e32 v0, 2, v180
	v_and_b32_e32 v1, 3, v180
	v_lshrrev_b32_e32 v2, 5, v180
	v_lshlrev_b32_e32 v2, 1, v2
	v_xor_b32_e32 v1, v1, v2
	v_lshlrev_b32_e32 v1, 4, v1
	v_lshrrev_b32_e32 v3, 2, v0
	v_lshlrev_b32_e32 v3, 3, v3
	v_and_b32_e32 v4, 3, v0
	v_add_u32_e32 v3, v3, v4
	s_lshl_b32 s0, s92, 5
	v_add_u32_e32 v3, s0, v3
	v_lshl_add_u32 v10, v3, 8, v1
	v_add_u32_e32 v11, 64, v10
	v_add_u32_e32 v12, 0x400, v10
	v_add_u32_e32 v13, 0x440, v10
	s_lshr_b32 s1, s92, 1
	s_lshl_b32 s1, s1, 12
	s_and_b32 s2, s92, 1
	s_lshl_b32 s2, s2, 6
	s_add_i32 s1, s1, s2
	v_lshl_add_u32 v14, v0, 8, v1
	v_add_u32_e32 v14, s1, v14
	v_and_b32_e32 v5, 15, v180
	v_lshrrev_b32_e32 v6, 4, v180
	v_lshlrev_b32_e32 v7, 6, v5
	v_lshl_add_u32 v7, v6, 4, v7
	v_and_b32_e32 v8, 8, v5
	v_lshlrev_b32_e32 v8, 2, v8
	v_xor_b32_e32 v7, v7, v8
	s_lshl_b32 s38, s92, 12
	v_add_u32_e32 v15, s38, v7
	v_add_u32_e32 v16, s38, v7
	v_add_u32_e32 v16, 0x8000, v16
	v_add_u32_e32 v17, s38, v7
	v_add_u32_e32 v17, 0x10000, v17
	v_add_u32_e32 v29, s38, v7
	v_add_u32_e32 v29, 0x18000, v29
	v_add_u32_e32 v18, 0x20400, v7
	v_lshlrev_b32_e32 v9, 4, v6
	v_lshl_add_u32 v19, v5, 13, v9
	v_lshl_add_u32 v20, v5, 12, v9
	v_lshlrev_b32_e32 v21, 9, v5
	v_lshlrev_b32_e32 v22, 8, v5
	v_xor_b32_e32 v23, 16, v180
	v_lshlrev_b32_e32 v23, 2, v23
	v_xor_b32_e32 v24, 32, v180
	v_lshlrev_b32_e32 v24, 2, v24
	s_lshl_b32 s0, s92, 8
	s_add_i32 s0, s0, 0x24400
	v_lshl_add_u32 v25, v5, 2, s0
	v_lshlrev_b32_e32 v26, 2, v180
	v_add_u32_e32 v26, 0x24400, v26
	v_lshlrev_b32_e32 v27, 9, v180
	v_lshlrev_b32_e32 v28, 8, v180
	s_lshl_b32 s0, s33, 16
	s_add_u32 s20, s80, s0
	s_addc_u32 s21, s81, 0
	s_add_u32 s22, s20, 0x25000000
	s_addc_u32 s23, s21, 0
	s_add_u32 s20, s20, 0x27000000
	s_addc_u32 s21, s21, 0
	s_lshr_b32 s1, s33, 1
	s_and_b32 s2, s1, 127
	s_and_b32 s3, s1, 63
	s_lshl_b32 s4, s2, 16
	s_add_u32 s34, s80, s4
	s_addc_u32 s35, s81, 0
	s_add_u32 s34, s34, 0x2f000000
	s_addc_u32 s35, s35, 0
	s_lshl_b32 s4, s3, 16
	s_add_u32 s36, s80, s4
	s_addc_u32 s37, s81, 0
	s_add_u32 s36, s36, 0x2f800000
	s_addc_u32 s37, s37, 0
	s_and_b32 s4, s33, 1
	s_lshl_b32 s4, s4, 3
	s_add_i32 s4, s4, s92
	s_mul_i32 s4, s4, 0x500000
	s_add_i32 s4, s4, 0x34000000
	s_add_i32 s5, s2, 0x4000
	s_lshl_b32 s6, s5, 6
	s_add_u32 s6, s6, s4
	s_add_u32 s24, s80, s6
	s_addc_u32 s25, s81, 0
	s_lshl_b32 s6, s5, 2
	s_add_i32 s6, s6, 0xa0000
	s_add_u32 s28, s80, s6
	s_addc_u32 s29, s81, 0
	s_lshr_b32 s5, s33, 7
	s_lshl_b32 s5, s5, 12
	s_add_i32 s5, s5, s3
	s_lshl_b32 s6, s5, 6
	s_add_u32 s6, s6, s4
	s_add_u32 s26, s80, s6
	s_addc_u32 s27, s81, 0
	s_lshl_b32 s6, s5, 2
	s_add_i32 s6, s6, 0xa0000
	s_add_u32 s30, s80, s6
	s_addc_u32 s31, s81, 0
	s_lshl_b32 s39, s92, 10
	s_add_i32 s39, s39, 0x20400
	s_add_u32 s0, s34, 0x0
	s_addc_u32 s1, s35, 0
	s_add_i32 m0, s39, 0x0
	s_nop 0
	global_load_lds_dwordx4 v14, s[0:1]
	s_add_u32 s0, s34, 0x80
	s_addc_u32 s1, s35, 0
	s_add_i32 m0, s39, 0x2000
	s_nop 0
	global_load_lds_dwordx4 v14, s[0:1]
	s_add_u32 s0, s20, 0x0
	s_addc_u32 s1, s21, 0
	s_add_i32 m0, s38, 0x0
	s_nop 0
	global_load_lds_dwordx4 v10, s[0:1]
	s_add_i32 m0, s38, 0x400
	s_nop 0
	global_load_lds_dwordx4 v11, s[0:1]
	s_add_i32 m0, s38, 0x800
	s_nop 0
	global_load_lds_dwordx4 v12, s[0:1]
	s_add_i32 m0, s38, 0xc00
	s_nop 0
	global_load_lds_dwordx4 v13, s[0:1]
	s_add_u32 s0, s20, 0x80
	s_addc_u32 s1, s21, 0
	s_add_i32 m0, s38, 0x8000
	s_nop 0
	global_load_lds_dwordx4 v10, s[0:1]
	s_add_i32 m0, s38, 0x8400
	s_nop 0
	global_load_lds_dwordx4 v11, s[0:1]
	s_add_i32 m0, s38, 0x8800
	s_nop 0
	global_load_lds_dwordx4 v12, s[0:1]
	s_add_i32 m0, s38, 0x8c00
	s_nop 0
	global_load_lds_dwordx4 v13, s[0:1]
	s_add_u32 s0, s20, 0x1000000
	s_addc_u32 s1, s21, 0
	s_add_i32 m0, s38, 0x10000
	s_nop 0
	global_load_lds_dwordx4 v10, s[0:1]
	s_add_i32 m0, s38, 0x10400
	s_nop 0
	global_load_lds_dwordx4 v11, s[0:1]
	s_add_i32 m0, s38, 0x10800
	s_nop 0
	global_load_lds_dwordx4 v12, s[0:1]
	s_add_i32 m0, s38, 0x10c00
	s_nop 0
	global_load_lds_dwordx4 v13, s[0:1]
	s_waitcnt vmcnt(8)
	s_barrier
	ds_read_b128 v[32:35], v18
	ds_read_b128 v[36:39], v18 offset:1024
	ds_read_b128 v[40:43], v18 offset:2048
	ds_read_b128 v[44:47], v18 offset:3072
	ds_read_b128 v[48:51], v18 offset:4096
	ds_read_b128 v[52:55], v18 offset:5120
	ds_read_b128 v[56:59], v18 offset:6144
	ds_read_b128 v[60:63], v18 offset:7168
	ds_read_b128 v[64:67], v18 offset:8192
	ds_read_b128 v[68:71], v18 offset:9216
	ds_read_b128 v[72:75], v18 offset:10240
	ds_read_b128 v[76:79], v18 offset:11264
	ds_read_b128 v[80:83], v18 offset:12288
	ds_read_b128 v[84:87], v18 offset:13312
	ds_read_b128 v[88:91], v18 offset:14336
	ds_read_b128 v[92:95], v18 offset:15360
	ds_read_b128 v[96:99], v15
	ds_read_b128 v[100:103], v15 offset:1024
	ds_read_b128 v[104:107], v15 offset:2048
	ds_read_b128 v[108:111], v15 offset:3072
	s_waitcnt lgkmcnt(0)
	s_setprio 1
	v_mfma_f32_16x16x32_bf16 v[128:131], v[96:99], v[32:35], 0
	v_mfma_f32_16x16x32_bf16 v[132:135], v[104:107], v[32:35], 0
	v_mfma_f32_16x16x32_bf16 v[136:139], v[96:99], v[40:43], 0
	v_mfma_f32_16x16x32_bf16 v[140:143], v[104:107], v[40:43], 0
	v_mfma_f32_16x16x32_bf16 v[144:147], v[96:99], v[48:51], 0
	v_mfma_f32_16x16x32_bf16 v[148:151], v[104:107], v[48:51], 0
	v_mfma_f32_16x16x32_bf16 v[152:155], v[96:99], v[56:59], 0
	v_mfma_f32_16x16x32_bf16 v[156:159], v[104:107], v[56:59], 0
	v_mfma_f32_16x16x32_bf16 v[128:131], v[100:103], v[36:39], v[128:131]
	v_mfma_f32_16x16x32_bf16 v[132:135], v[108:111], v[36:39], v[132:135]
	v_mfma_f32_16x16x32_bf16 v[136:139], v[100:103], v[44:47], v[136:139]
	v_mfma_f32_16x16x32_bf16 v[140:143], v[108:111], v[44:47], v[140:143]
	v_mfma_f32_16x16x32_bf16 v[144:147], v[100:103], v[52:55], v[144:147]
	v_mfma_f32_16x16x32_bf16 v[148:151], v[108:111], v[52:55], v[148:151]
	v_mfma_f32_16x16x32_bf16 v[152:155], v[100:103], v[60:63], v[152:155]
	v_mfma_f32_16x16x32_bf16 v[156:159], v[108:111], v[60:63], v[156:159]
	s_setprio 0
	s_add_u32 s0, s20, 0x1000080
	s_addc_u32 s1, s21, 0
	s_add_i32 m0, s38, 0x18000
	s_nop 0
	global_load_lds_dwordx4 v10, s[0:1]
	s_add_i32 m0, s38, 0x18400
	s_nop 0
	global_load_lds_dwordx4 v11, s[0:1]
	s_add_i32 m0, s38, 0x18800
	s_nop 0
	global_load_lds_dwordx4 v12, s[0:1]
	s_add_i32 m0, s38, 0x18c00
	s_nop 0
	global_load_lds_dwordx4 v13, s[0:1]
	s_waitcnt vmcnt(8)
	s_barrier
	ds_read_b128 v[96:99], v16
	ds_read_b128 v[100:103], v16 offset:1024
	ds_read_b128 v[104:107], v16 offset:2048
	ds_read_b128 v[108:111], v16 offset:3072
	s_waitcnt lgkmcnt(0)
	s_setprio 1
	v_mfma_f32_16x16x32_bf16 v[128:131], v[96:99], v[64:67], v[128:131]
	v_mfma_f32_16x16x32_bf16 v[132:135], v[104:107], v[64:67], v[132:135]
	v_mfma_f32_16x16x32_bf16 v[136:139], v[96:99], v[72:75], v[136:139]
	v_mfma_f32_16x16x32_bf16 v[140:143], v[104:107], v[72:75], v[140:143]
	v_mfma_f32_16x16x32_bf16 v[144:147], v[96:99], v[80:83], v[144:147]
	v_mfma_f32_16x16x32_bf16 v[148:151], v[104:107], v[80:83], v[148:151]
	v_mfma_f32_16x16x32_bf16 v[152:155], v[96:99], v[88:91], v[152:155]
	v_mfma_f32_16x16x32_bf16 v[156:159], v[104:107], v[88:91], v[156:159]
	v_mfma_f32_16x16x32_bf16 v[128:131], v[100:103], v[68:71], v[128:131]
	v_mfma_f32_16x16x32_bf16 v[132:135], v[108:111], v[68:71], v[132:135]
	v_mfma_f32_16x16x32_bf16 v[136:139], v[100:103], v[76:79], v[136:139]
	v_mfma_f32_16x16x32_bf16 v[140:143], v[108:111], v[76:79], v[140:143]
	v_mfma_f32_16x16x32_bf16 v[144:147], v[100:103], v[84:87], v[144:147]
	v_mfma_f32_16x16x32_bf16 v[148:151], v[108:111], v[84:87], v[148:151]
	v_mfma_f32_16x16x32_bf16 v[152:155], v[100:103], v[92:95], v[152:155]
	v_mfma_f32_16x16x32_bf16 v[156:159], v[108:111], v[92:95], v[156:159]
	s_setprio 0
	s_add_u32 s0, s20, 0x2000000
	s_addc_u32 s1, s21, 0
	s_add_i32 m0, s38, 0x0
	s_nop 0
	global_load_lds_dwordx4 v10, s[0:1]
	s_add_i32 m0, s38, 0x400
	s_nop 0
	global_load_lds_dwordx4 v11, s[0:1]
	s_add_i32 m0, s38, 0x800
	s_nop 0
	global_load_lds_dwordx4 v12, s[0:1]
	s_add_i32 m0, s38, 0xc00
	s_nop 0
	global_load_lds_dwordx4 v13, s[0:1]
	s_nop 7
	v_mul_f32_e32 v160, v128, v128
	v_fmac_f32_e32 v160, v129, v129
	v_fmac_f32_e32 v160, v130, v130
	v_fmac_f32_e32 v160, v131, v131
	v_fmac_f32_e32 v160, v132, v132
	v_fmac_f32_e32 v160, v133, v133
	v_fmac_f32_e32 v160, v134, v134
	v_fmac_f32_e32 v160, v135, v135
	v_cvt_pk_bf16_f32 v184, v128, v129
	v_cvt_pk_bf16_f32 v185, v130, v131
	v_cvt_pk_bf16_f32 v186, v132, v133
	v_cvt_pk_bf16_f32 v187, v134, v135
	s_add_u32 s2, s24, 0x0
	s_addc_u32 s3, s25, 0
	global_store_dwordx4 v19, v[184:187], s[2:3]
	v_mul_f32_e32 v161, v136, v136
	v_fmac_f32_e32 v161, v137, v137
	v_fmac_f32_e32 v161, v138, v138
	v_fmac_f32_e32 v161, v139, v139
	v_fmac_f32_e32 v161, v140, v140
	v_fmac_f32_e32 v161, v141, v141
	v_fmac_f32_e32 v161, v142, v142
	v_fmac_f32_e32 v161, v143, v143
	v_cvt_pk_bf16_f32 v188, v136, v137
	v_cvt_pk_bf16_f32 v189, v138, v139
	v_cvt_pk_bf16_f32 v190, v140, v141
	v_cvt_pk_bf16_f32 v191, v142, v143
	s_add_u32 s2, s24, 0x20000
	s_addc_u32 s3, s25, 0
	global_store_dwordx4 v19, v[188:191], s[2:3]
	v_mul_f32_e32 v162, v144, v144
	v_fmac_f32_e32 v162, v145, v145
	v_fmac_f32_e32 v162, v146, v146
	v_fmac_f32_e32 v162, v147, v147
	v_fmac_f32_e32 v162, v148, v148
	v_fmac_f32_e32 v162, v149, v149
	v_fmac_f32_e32 v162, v150, v150
	v_fmac_f32_e32 v162, v151, v151
	v_cvt_pk_bf16_f32 v192, v144, v145
	v_cvt_pk_bf16_f32 v193, v146, v147
	v_cvt_pk_bf16_f32 v194, v148, v149
	v_cvt_pk_bf16_f32 v195, v150, v151
	s_add_u32 s2, s24, 0x40000
	s_addc_u32 s3, s25, 0
	global_store_dwordx4 v19, v[192:195], s[2:3]
	v_mul_f32_e32 v163, v152, v152
	v_fmac_f32_e32 v163, v153, v153
	v_fmac_f32_e32 v163, v154, v154
	v_fmac_f32_e32 v163, v155, v155
	v_fmac_f32_e32 v163, v156, v156
	v_fmac_f32_e32 v163, v157, v157
	v_fmac_f32_e32 v163, v158, v158
	v_fmac_f32_e32 v163, v159, v159
	v_cvt_pk_bf16_f32 v196, v152, v153
	v_cvt_pk_bf16_f32 v197, v154, v155
	v_cvt_pk_bf16_f32 v198, v156, v157
	v_cvt_pk_bf16_f32 v199, v158, v159
	s_add_u32 s2, s24, 0x60000
	s_addc_u32 s3, s25, 0
	global_store_dwordx4 v19, v[196:199], s[2:3]
	ds_bpermute_b32 v168, v23, v160
	ds_bpermute_b32 v169, v23, v161
	ds_bpermute_b32 v170, v23, v162
	ds_bpermute_b32 v171, v23, v163
	s_waitcnt lgkmcnt(0)
	v_add_f32_e32 v160, v160, v168
	v_add_f32_e32 v161, v161, v169
	v_add_f32_e32 v162, v162, v170
	v_add_f32_e32 v163, v163, v171
	ds_bpermute_b32 v168, v24, v160
	ds_bpermute_b32 v169, v24, v161
	ds_bpermute_b32 v170, v24, v162
	ds_bpermute_b32 v171, v24, v163
	s_waitcnt lgkmcnt(0)
	v_add_f32_e32 v160, v160, v168
	v_add_f32_e32 v161, v161, v169
	v_add_f32_e32 v162, v162, v170
	v_add_f32_e32 v163, v163, v171
	s_mov_b64 exec, 0xffff
	ds_write_b32 v25, v160
	ds_write_b32 v25, v161 offset:64
	ds_write_b32 v25, v162 offset:128
	ds_write_b32 v25, v163 offset:192
	s_mov_b64 exec, -1
	s_waitcnt lgkmcnt(0)
	s_waitcnt vmcnt(12)
	s_barrier
	s_cmp_lg_u32 s92, 0
	s_cbranch_scc1 .Lfftb_nored0
	ds_read_b32 v168, v26
	ds_read_b32 v169, v26 offset:256
	ds_read_b32 v170, v26 offset:512
	ds_read_b32 v171, v26 offset:768
	ds_read_b32 v172, v26 offset:1024
	ds_read_b32 v173, v26 offset:1280
	ds_read_b32 v174, v26 offset:1536
	ds_read_b32 v175, v26 offset:1792
	s_waitcnt lgkmcnt(0)
	v_add_f32_e32 v168, v168, v169
	v_add_f32_e32 v170, v170, v171
	v_add_f32_e32 v172, v172, v173
	v_add_f32_e32 v174, v174, v175
	v_add_f32_e32 v168, v168, v170
	v_add_f32_e32 v172, v172, v174
	v_add_f32_e32 v168, v168, v172
	s_add_u32 s2, s28, 0x0
	s_addc_u32 s3, s29, 0
	global_atomic_add_f32 v27, v168, s[2:3]
.Lfftb_nored0:
	ds_read_b128 v[96:99], v17
	ds_read_b128 v[100:103], v17 offset:1024
	ds_read_b128 v[104:107], v17 offset:2048
	ds_read_b128 v[108:111], v17 offset:3072
	s_waitcnt lgkmcnt(0)
	s_setprio 1
	v_mfma_f32_16x16x32_bf16 v[128:131], v[96:99], v[32:35], 0
	v_mfma_f32_16x16x32_bf16 v[132:135], v[104:107], v[32:35], 0
	v_mfma_f32_16x16x32_bf16 v[136:139], v[96:99], v[40:43], 0
	v_mfma_f32_16x16x32_bf16 v[140:143], v[104:107], v[40:43], 0
	v_mfma_f32_16x16x32_bf16 v[144:147], v[96:99], v[48:51], 0
	v_mfma_f32_16x16x32_bf16 v[148:151], v[104:107], v[48:51], 0
	v_mfma_f32_16x16x32_bf16 v[152:155], v[96:99], v[56:59], 0
	v_mfma_f32_16x16x32_bf16 v[156:159], v[104:107], v[56:59], 0
	v_mfma_f32_16x16x32_bf16 v[128:131], v[100:103], v[36:39], v[128:131]
	v_mfma_f32_16x16x32_bf16 v[132:135], v[108:111], v[36:39], v[132:135]
	v_mfma_f32_16x16x32_bf16 v[136:139], v[100:103], v[44:47], v[136:139]
	v_mfma_f32_16x16x32_bf16 v[140:143], v[108:111], v[44:47], v[140:143]
	v_mfma_f32_16x16x32_bf16 v[144:147], v[100:103], v[52:55], v[144:147]
	v_mfma_f32_16x16x32_bf16 v[148:151], v[108:111], v[52:55], v[148:151]
	v_mfma_f32_16x16x32_bf16 v[152:155], v[100:103], v[60:63], v[152:155]
	v_mfma_f32_16x16x32_bf16 v[156:159], v[108:111], v[60:63], v[156:159]
	s_setprio 0
	s_add_u32 s0, s20, 0x2000080
	s_addc_u32 s1, s21, 0
	s_add_i32 m0, s38, 0x8000
	s_nop 0
	global_load_lds_dwordx4 v10, s[0:1]
	s_add_i32 m0, s38, 0x8400
	s_nop 0
	global_load_lds_dwordx4 v11, s[0:1]
	s_add_i32 m0, s38, 0x8800
	s_nop 0
	global_load_lds_dwordx4 v12, s[0:1]
	s_add_i32 m0, s38, 0x8c00
	s_nop 0
	global_load_lds_dwordx4 v13, s[0:1]
	s_waitcnt vmcnt(12)
	s_barrier
	ds_read_b128 v[96:99], v29
	ds_read_b128 v[100:103], v29 offset:1024
	ds_read_b128 v[104:107], v29 offset:2048
	ds_read_b128 v[108:111], v29 offset:3072
	s_waitcnt lgkmcnt(0)
	s_setprio 1
	v_mfma_f32_16x16x32_bf16 v[128:131], v[96:99], v[64:67], v[128:131]
	v_mfma_f32_16x16x32_bf16 v[132:135], v[104:107], v[64:67], v[132:135]
	v_mfma_f32_16x16x32_bf16 v[136:139], v[96:99], v[72:75], v[136:139]
	v_mfma_f32_16x16x32_bf16 v[140:143], v[104:107], v[72:75], v[140:143]
	v_mfma_f32_16x16x32_bf16 v[144:147], v[96:99], v[80:83], v[144:147]
	v_mfma_f32_16x16x32_bf16 v[148:151], v[104:107], v[80:83], v[148:151]
	v_mfma_f32_16x16x32_bf16 v[152:155], v[96:99], v[88:91], v[152:155]
	v_mfma_f32_16x16x32_bf16 v[156:159], v[104:107], v[88:91], v[156:159]
	v_mfma_f32_16x16x32_bf16 v[128:131], v[100:103], v[68:71], v[128:131]
	v_mfma_f32_16x16x32_bf16 v[132:135], v[108:111], v[68:71], v[132:135]
	v_mfma_f32_16x16x32_bf16 v[136:139], v[100:103], v[76:79], v[136:139]
	v_mfma_f32_16x16x32_bf16 v[140:143], v[108:111], v[76:79], v[140:143]
	v_mfma_f32_16x16x32_bf16 v[144:147], v[100:103], v[84:87], v[144:147]
	v_mfma_f32_16x16x32_bf16 v[148:151], v[108:111], v[84:87], v[148:151]
	v_mfma_f32_16x16x32_bf16 v[152:155], v[100:103], v[92:95], v[152:155]
	v_mfma_f32_16x16x32_bf16 v[156:159], v[108:111], v[92:95], v[156:159]
	s_setprio 0
	s_add_u32 s0, s20, 0x3000000
	s_addc_u32 s1, s21, 0
	s_add_i32 m0, s38, 0x10000
	s_nop 0
	global_load_lds_dwordx4 v10, s[0:1]
	s_add_i32 m0, s38, 0x10400
	s_nop 0
	global_load_lds_dwordx4 v11, s[0:1]
	s_add_i32 m0, s38, 0x10800
	s_nop 0
	global_load_lds_dwordx4 v12, s[0:1]
	s_add_i32 m0, s38, 0x10c00
	s_nop 0
	global_load_lds_dwordx4 v13, s[0:1]
	s_nop 7
	v_mul_f32_e32 v160, v128, v128
	v_fmac_f32_e32 v160, v129, v129
	v_fmac_f32_e32 v160, v130, v130
	v_fmac_f32_e32 v160, v131, v131
	v_fmac_f32_e32 v160, v132, v132
	v_fmac_f32_e32 v160, v133, v133
	v_fmac_f32_e32 v160, v134, v134
	v_fmac_f32_e32 v160, v135, v135
	v_cvt_pk_bf16_f32 v184, v128, v129
	v_cvt_pk_bf16_f32 v185, v130, v131
	v_cvt_pk_bf16_f32 v186, v132, v133
	v_cvt_pk_bf16_f32 v187, v134, v135
	s_add_u32 s2, s24, 0x80000
	s_addc_u32 s3, s25, 0
	global_store_dwordx4 v19, v[184:187], s[2:3]
	v_mul_f32_e32 v161, v136, v136
	v_fmac_f32_e32 v161, v137, v137
	v_fmac_f32_e32 v161, v138, v138
	v_fmac_f32_e32 v161, v139, v139
	v_fmac_f32_e32 v161, v140, v140
	v_fmac_f32_e32 v161, v141, v141
	v_fmac_f32_e32 v161, v142, v142
	v_fmac_f32_e32 v161, v143, v143
	v_cvt_pk_bf16_f32 v188, v136, v137
	v_cvt_pk_bf16_f32 v189, v138, v139
	v_cvt_pk_bf16_f32 v190, v140, v141
	v_cvt_pk_bf16_f32 v191, v142, v143
	s_add_u32 s2, s24, 0xa0000
	s_addc_u32 s3, s25, 0
	global_store_dwordx4 v19, v[188:191], s[2:3]
	v_mul_f32_e32 v162, v144, v144
	v_fmac_f32_e32 v162, v145, v145
	v_fmac_f32_e32 v162, v146, v146
	v_fmac_f32_e32 v162, v147, v147
	v_fmac_f32_e32 v162, v148, v148
	v_fmac_f32_e32 v162, v149, v149
	v_fmac_f32_e32 v162, v150, v150
	v_fmac_f32_e32 v162, v151, v151
	v_cvt_pk_bf16_f32 v192, v144, v145
	v_cvt_pk_bf16_f32 v193, v146, v147
	v_cvt_pk_bf16_f32 v194, v148, v149
	v_cvt_pk_bf16_f32 v195, v150, v151
	s_add_u32 s2, s24, 0xc0000
	s_addc_u32 s3, s25, 0
	global_store_dwordx4 v19, v[192:195], s[2:3]
	v_mul_f32_e32 v163, v152, v152
	v_fmac_f32_e32 v163, v153, v153
	v_fmac_f32_e32 v163, v154, v154
	v_fmac_f32_e32 v163, v155, v155
	v_fmac_f32_e32 v163, v156, v156
	v_fmac_f32_e32 v163, v157, v157
	v_fmac_f32_e32 v163, v158, v158
	v_fmac_f32_e32 v163, v159, v159
	v_cvt_pk_bf16_f32 v196, v152, v153
	v_cvt_pk_bf16_f32 v197, v154, v155
	v_cvt_pk_bf16_f32 v198, v156, v157
	v_cvt_pk_bf16_f32 v199, v158, v159
	s_add_u32 s2, s24, 0xe0000
	s_addc_u32 s3, s25, 0
	global_store_dwordx4 v19, v[196:199], s[2:3]
	ds_bpermute_b32 v168, v23, v160
	ds_bpermute_b32 v169, v23, v161
	ds_bpermute_b32 v170, v23, v162
	ds_bpermute_b32 v171, v23, v163
	s_waitcnt lgkmcnt(0)
	v_add_f32_e32 v160, v160, v168
	v_add_f32_e32 v161, v161, v169
	v_add_f32_e32 v162, v162, v170
	v_add_f32_e32 v163, v163, v171
	ds_bpermute_b32 v168, v24, v160
	ds_bpermute_b32 v169, v24, v161
	ds_bpermute_b32 v170, v24, v162
	ds_bpermute_b32 v171, v24, v163
	s_waitcnt lgkmcnt(0)
	v_add_f32_e32 v160, v160, v168
	v_add_f32_e32 v161, v161, v169
	v_add_f32_e32 v162, v162, v170
	v_add_f32_e32 v163, v163, v171
	s_mov_b64 exec, 0xffff
	ds_write_b32 v25, v160
	ds_write_b32 v25, v161 offset:64
	ds_write_b32 v25, v162 offset:128
	ds_write_b32 v25, v163 offset:192
	s_mov_b64 exec, -1
	s_waitcnt lgkmcnt(0)
	s_waitcnt vmcnt(16)
	s_barrier
	s_cmp_lg_u32 s92, 0
	s_cbranch_scc1 .Lfftb_nored1
	ds_read_b32 v168, v26
	ds_read_b32 v169, v26 offset:256
	ds_read_b32 v170, v26 offset:512
	ds_read_b32 v171, v26 offset:768
	ds_read_b32 v172, v26 offset:1024
	ds_read_b32 v173, v26 offset:1280
	ds_read_b32 v174, v26 offset:1536
	ds_read_b32 v175, v26 offset:1792
	s_waitcnt lgkmcnt(0)
	v_add_f32_e32 v168, v168, v169
	v_add_f32_e32 v170, v170, v171
	v_add_f32_e32 v172, v172, v173
	v_add_f32_e32 v174, v174, v175
	v_add_f32_e32 v168, v168, v170
	v_add_f32_e32 v172, v172, v174
	v_add_f32_e32 v168, v168, v172
	s_add_u32 s2, s28, 0x8000
	s_addc_u32 s3, s29, 0
	global_atomic_add_f32 v27, v168, s[2:3]
.Lfftb_nored1:
	ds_read_b128 v[96:99], v15
	ds_read_b128 v[100:103], v15 offset:1024
	ds_read_b128 v[104:107], v15 offset:2048
	ds_read_b128 v[108:111], v15 offset:3072
	s_waitcnt lgkmcnt(0)
	s_setprio 1
	v_mfma_f32_16x16x32_bf16 v[128:131], v[96:99], v[32:35], 0
	v_mfma_f32_16x16x32_bf16 v[132:135], v[104:107], v[32:35], 0
	v_mfma_f32_16x16x32_bf16 v[136:139], v[96:99], v[40:43], 0
	v_mfma_f32_16x16x32_bf16 v[140:143], v[104:107], v[40:43], 0
	v_mfma_f32_16x16x32_bf16 v[144:147], v[96:99], v[48:51], 0
	v_mfma_f32_16x16x32_bf16 v[148:151], v[104:107], v[48:51], 0
	v_mfma_f32_16x16x32_bf16 v[152:155], v[96:99], v[56:59], 0
	v_mfma_f32_16x16x32_bf16 v[156:159], v[104:107], v[56:59], 0
	v_mfma_f32_16x16x32_bf16 v[128:131], v[100:103], v[36:39], v[128:131]
	v_mfma_f32_16x16x32_bf16 v[132:135], v[108:111], v[36:39], v[132:135]
	v_mfma_f32_16x16x32_bf16 v[136:139], v[100:103], v[44:47], v[136:139]
	v_mfma_f32_16x16x32_bf16 v[140:143], v[108:111], v[44:47], v[140:143]
	v_mfma_f32_16x16x32_bf16 v[144:147], v[100:103], v[52:55], v[144:147]
	v_mfma_f32_16x16x32_bf16 v[148:151], v[108:111], v[52:55], v[148:151]
	v_mfma_f32_16x16x32_bf16 v[152:155], v[100:103], v[60:63], v[152:155]
	v_mfma_f32_16x16x32_bf16 v[156:159], v[108:111], v[60:63], v[156:159]
	s_setprio 0
	s_add_u32 s0, s20, 0x3000080
	s_addc_u32 s1, s21, 0
	s_add_i32 m0, s38, 0x18000
	s_nop 0
	global_load_lds_dwordx4 v10, s[0:1]
	s_add_i32 m0, s38, 0x18400
	s_nop 0
	global_load_lds_dwordx4 v11, s[0:1]
	s_add_i32 m0, s38, 0x18800
	s_nop 0
	global_load_lds_dwordx4 v12, s[0:1]
	s_add_i32 m0, s38, 0x18c00
	s_nop 0
	global_load_lds_dwordx4 v13, s[0:1]
	s_waitcnt vmcnt(12)
	s_barrier
	ds_read_b128 v[96:99], v16
	ds_read_b128 v[100:103], v16 offset:1024
	ds_read_b128 v[104:107], v16 offset:2048
	ds_read_b128 v[108:111], v16 offset:3072
	s_waitcnt lgkmcnt(0)
	s_setprio 1
	v_mfma_f32_16x16x32_bf16 v[128:131], v[96:99], v[64:67], v[128:131]
	v_mfma_f32_16x16x32_bf16 v[132:135], v[104:107], v[64:67], v[132:135]
	v_mfma_f32_16x16x32_bf16 v[136:139], v[96:99], v[72:75], v[136:139]
	v_mfma_f32_16x16x32_bf16 v[140:143], v[104:107], v[72:75], v[140:143]
	v_mfma_f32_16x16x32_bf16 v[144:147], v[96:99], v[80:83], v[144:147]
	v_mfma_f32_16x16x32_bf16 v[148:151], v[104:107], v[80:83], v[148:151]
	v_mfma_f32_16x16x32_bf16 v[152:155], v[96:99], v[88:91], v[152:155]
	v_mfma_f32_16x16x32_bf16 v[156:159], v[104:107], v[88:91], v[156:159]
	v_mfma_f32_16x16x32_bf16 v[128:131], v[100:103], v[68:71], v[128:131]
	v_mfma_f32_16x16x32_bf16 v[132:135], v[108:111], v[68:71], v[132:135]
	v_mfma_f32_16x16x32_bf16 v[136:139], v[100:103], v[76:79], v[136:139]
	v_mfma_f32_16x16x32_bf16 v[140:143], v[108:111], v[76:79], v[140:143]
	v_mfma_f32_16x16x32_bf16 v[144:147], v[100:103], v[84:87], v[144:147]
	v_mfma_f32_16x16x32_bf16 v[148:151], v[108:111], v[84:87], v[148:151]
	v_mfma_f32_16x16x32_bf16 v[152:155], v[100:103], v[92:95], v[152:155]
	v_mfma_f32_16x16x32_bf16 v[156:159], v[108:111], v[92:95], v[156:159]
	s_setprio 0
	s_add_u32 s0, s20, 0x4000000
	s_addc_u32 s1, s21, 0
	s_add_i32 m0, s38, 0x0
	s_nop 0
	global_load_lds_dwordx4 v10, s[0:1]
	s_add_i32 m0, s38, 0x400
	s_nop 0
	global_load_lds_dwordx4 v11, s[0:1]
	s_add_i32 m0, s38, 0x800
	s_nop 0
	global_load_lds_dwordx4 v12, s[0:1]
	s_add_i32 m0, s38, 0xc00
	s_nop 0
	global_load_lds_dwordx4 v13, s[0:1]
	s_nop 7
	v_mul_f32_e32 v160, v128, v128
	v_fmac_f32_e32 v160, v129, v129
	v_fmac_f32_e32 v160, v130, v130
	v_fmac_f32_e32 v160, v131, v131
	v_fmac_f32_e32 v160, v132, v132
	v_fmac_f32_e32 v160, v133, v133
	v_fmac_f32_e32 v160, v134, v134
	v_fmac_f32_e32 v160, v135, v135
	v_cvt_pk_bf16_f32 v184, v128, v129
	v_cvt_pk_bf16_f32 v185, v130, v131
	v_cvt_pk_bf16_f32 v186, v132, v133
	v_cvt_pk_bf16_f32 v187, v134, v135
	s_add_u32 s2, s24, 0x100000
	s_addc_u32 s3, s25, 0
	global_store_dwordx4 v19, v[184:187], s[2:3]
	v_mul_f32_e32 v161, v136, v136
	v_fmac_f32_e32 v161, v137, v137
	v_fmac_f32_e32 v161, v138, v138
	v_fmac_f32_e32 v161, v139, v139
	v_fmac_f32_e32 v161, v140, v140
	v_fmac_f32_e32 v161, v141, v141
	v_fmac_f32_e32 v161, v142, v142
	v_fmac_f32_e32 v161, v143, v143
	v_cvt_pk_bf16_f32 v188, v136, v137
	v_cvt_pk_bf16_f32 v189, v138, v139
	v_cvt_pk_bf16_f32 v190, v140, v141
	v_cvt_pk_bf16_f32 v191, v142, v143
	s_add_u32 s2, s24, 0x120000
	s_addc_u32 s3, s25, 0
	global_store_dwordx4 v19, v[188:191], s[2:3]
	v_mul_f32_e32 v162, v144, v144
	v_fmac_f32_e32 v162, v145, v145
	v_fmac_f32_e32 v162, v146, v146
	v_fmac_f32_e32 v162, v147, v147
	v_fmac_f32_e32 v162, v148, v148
	v_fmac_f32_e32 v162, v149, v149
	v_fmac_f32_e32 v162, v150, v150
	v_fmac_f32_e32 v162, v151, v151
	v_cvt_pk_bf16_f32 v192, v144, v145
	v_cvt_pk_bf16_f32 v193, v146, v147
	v_cvt_pk_bf16_f32 v194, v148, v149
	v_cvt_pk_bf16_f32 v195, v150, v151
	s_add_u32 s2, s24, 0x140000
	s_addc_u32 s3, s25, 0
	global_store_dwordx4 v19, v[192:195], s[2:3]
	v_mul_f32_e32 v163, v152, v152
	v_fmac_f32_e32 v163, v153, v153
	v_fmac_f32_e32 v163, v154, v154
	v_fmac_f32_e32 v163, v155, v155
	v_fmac_f32_e32 v163, v156, v156
	v_fmac_f32_e32 v163, v157, v157
	v_fmac_f32_e32 v163, v158, v158
	v_fmac_f32_e32 v163, v159, v159
	v_cvt_pk_bf16_f32 v196, v152, v153
	v_cvt_pk_bf16_f32 v197, v154, v155
	v_cvt_pk_bf16_f32 v198, v156, v157
	v_cvt_pk_bf16_f32 v199, v158, v159
	s_add_u32 s2, s24, 0x160000
	s_addc_u32 s3, s25, 0
	global_store_dwordx4 v19, v[196:199], s[2:3]
	ds_bpermute_b32 v168, v23, v160
	ds_bpermute_b32 v169, v23, v161
	ds_bpermute_b32 v170, v23, v162
	ds_bpermute_b32 v171, v23, v163
	s_waitcnt lgkmcnt(0)
	v_add_f32_e32 v160, v160, v168
	v_add_f32_e32 v161, v161, v169
	v_add_f32_e32 v162, v162, v170
	v_add_f32_e32 v163, v163, v171
	ds_bpermute_b32 v168, v24, v160
	ds_bpermute_b32 v169, v24, v161
	ds_bpermute_b32 v170, v24, v162
	ds_bpermute_b32 v171, v24, v163
	s_waitcnt lgkmcnt(0)
	v_add_f32_e32 v160, v160, v168
	v_add_f32_e32 v161, v161, v169
	v_add_f32_e32 v162, v162, v170
	v_add_f32_e32 v163, v163, v171
	s_mov_b64 exec, 0xffff
	ds_write_b32 v25, v160
	ds_write_b32 v25, v161 offset:64
	ds_write_b32 v25, v162 offset:128
	ds_write_b32 v25, v163 offset:192
	s_mov_b64 exec, -1
	s_waitcnt lgkmcnt(0)
	s_waitcnt vmcnt(16)
	s_barrier
	s_cmp_lg_u32 s92, 0
	s_cbranch_scc1 .Lfftb_nored2
	ds_read_b32 v168, v26
	ds_read_b32 v169, v26 offset:256
	ds_read_b32 v170, v26 offset:512
	ds_read_b32 v171, v26 offset:768
	ds_read_b32 v172, v26 offset:1024
	ds_read_b32 v173, v26 offset:1280
	ds_read_b32 v174, v26 offset:1536
	ds_read_b32 v175, v26 offset:1792
	s_waitcnt lgkmcnt(0)
	v_add_f32_e32 v168, v168, v169
	v_add_f32_e32 v170, v170, v171
	v_add_f32_e32 v172, v172, v173
	v_add_f32_e32 v174, v174, v175
	v_add_f32_e32 v168, v168, v170
	v_add_f32_e32 v172, v172, v174
	v_add_f32_e32 v168, v168, v172
	s_add_u32 s2, s28, 0x10000
	s_addc_u32 s3, s29, 0
	global_atomic_add_f32 v27, v168, s[2:3]
.Lfftb_nored2:
	ds_read_b128 v[96:99], v17
	ds_read_b128 v[100:103], v17 offset:1024
	ds_read_b128 v[104:107], v17 offset:2048
	ds_read_b128 v[108:111], v17 offset:3072
	s_waitcnt lgkmcnt(0)
	s_setprio 1
	v_mfma_f32_16x16x32_bf16 v[128:131], v[96:99], v[32:35], 0
	v_mfma_f32_16x16x32_bf16 v[132:135], v[104:107], v[32:35], 0
	v_mfma_f32_16x16x32_bf16 v[136:139], v[96:99], v[40:43], 0
	v_mfma_f32_16x16x32_bf16 v[140:143], v[104:107], v[40:43], 0
	v_mfma_f32_16x16x32_bf16 v[144:147], v[96:99], v[48:51], 0
	v_mfma_f32_16x16x32_bf16 v[148:151], v[104:107], v[48:51], 0
	v_mfma_f32_16x16x32_bf16 v[152:155], v[96:99], v[56:59], 0
	v_mfma_f32_16x16x32_bf16 v[156:159], v[104:107], v[56:59], 0
	v_mfma_f32_16x16x32_bf16 v[128:131], v[100:103], v[36:39], v[128:131]
	v_mfma_f32_16x16x32_bf16 v[132:135], v[108:111], v[36:39], v[132:135]
	v_mfma_f32_16x16x32_bf16 v[136:139], v[100:103], v[44:47], v[136:139]
	v_mfma_f32_16x16x32_bf16 v[140:143], v[108:111], v[44:47], v[140:143]
	v_mfma_f32_16x16x32_bf16 v[144:147], v[100:103], v[52:55], v[144:147]
	v_mfma_f32_16x16x32_bf16 v[148:151], v[108:111], v[52:55], v[148:151]
	v_mfma_f32_16x16x32_bf16 v[152:155], v[100:103], v[60:63], v[152:155]
	v_mfma_f32_16x16x32_bf16 v[156:159], v[108:111], v[60:63], v[156:159]
	s_setprio 0
	s_add_u32 s0, s20, 0x4000080
	s_addc_u32 s1, s21, 0
	s_add_i32 m0, s38, 0x8000
	s_nop 0
	global_load_lds_dwordx4 v10, s[0:1]
	s_add_i32 m0, s38, 0x8400
	s_nop 0
	global_load_lds_dwordx4 v11, s[0:1]
	s_add_i32 m0, s38, 0x8800
	s_nop 0
	global_load_lds_dwordx4 v12, s[0:1]
	s_add_i32 m0, s38, 0x8c00
	s_nop 0
	global_load_lds_dwordx4 v13, s[0:1]
	s_waitcnt vmcnt(12)
	s_barrier
	ds_read_b128 v[96:99], v29
	ds_read_b128 v[100:103], v29 offset:1024
	ds_read_b128 v[104:107], v29 offset:2048
	ds_read_b128 v[108:111], v29 offset:3072
	s_waitcnt lgkmcnt(0)
	s_setprio 1
	v_mfma_f32_16x16x32_bf16 v[128:131], v[96:99], v[64:67], v[128:131]
	v_mfma_f32_16x16x32_bf16 v[132:135], v[104:107], v[64:67], v[132:135]
	v_mfma_f32_16x16x32_bf16 v[136:139], v[96:99], v[72:75], v[136:139]
	v_mfma_f32_16x16x32_bf16 v[140:143], v[104:107], v[72:75], v[140:143]
	v_mfma_f32_16x16x32_bf16 v[144:147], v[96:99], v[80:83], v[144:147]
	v_mfma_f32_16x16x32_bf16 v[148:151], v[104:107], v[80:83], v[148:151]
	v_mfma_f32_16x16x32_bf16 v[152:155], v[96:99], v[88:91], v[152:155]
	v_mfma_f32_16x16x32_bf16 v[156:159], v[104:107], v[88:91], v[156:159]
	v_mfma_f32_16x16x32_bf16 v[128:131], v[100:103], v[68:71], v[128:131]
	v_mfma_f32_16x16x32_bf16 v[132:135], v[108:111], v[68:71], v[132:135]
	v_mfma_f32_16x16x32_bf16 v[136:139], v[100:103], v[76:79], v[136:139]
	v_mfma_f32_16x16x32_bf16 v[140:143], v[108:111], v[76:79], v[140:143]
	v_mfma_f32_16x16x32_bf16 v[144:147], v[100:103], v[84:87], v[144:147]
	v_mfma_f32_16x16x32_bf16 v[148:151], v[108:111], v[84:87], v[148:151]
	v_mfma_f32_16x16x32_bf16 v[152:155], v[100:103], v[92:95], v[152:155]
	v_mfma_f32_16x16x32_bf16 v[156:159], v[108:111], v[92:95], v[156:159]
	s_setprio 0
	s_add_u32 s0, s20, 0x5000000
	s_addc_u32 s1, s21, 0
	s_add_i32 m0, s38, 0x10000
	s_nop 0
	global_load_lds_dwordx4 v10, s[0:1]
	s_add_i32 m0, s38, 0x10400
	s_nop 0
	global_load_lds_dwordx4 v11, s[0:1]
	s_add_i32 m0, s38, 0x10800
	s_nop 0
	global_load_lds_dwordx4 v12, s[0:1]
	s_add_i32 m0, s38, 0x10c00
	s_nop 0
	global_load_lds_dwordx4 v13, s[0:1]
	s_nop 7
	v_mul_f32_e32 v160, v128, v128
	v_fmac_f32_e32 v160, v129, v129
	v_fmac_f32_e32 v160, v130, v130
	v_fmac_f32_e32 v160, v131, v131
	v_fmac_f32_e32 v160, v132, v132
	v_fmac_f32_e32 v160, v133, v133
	v_fmac_f32_e32 v160, v134, v134
	v_fmac_f32_e32 v160, v135, v135
	v_cvt_pk_bf16_f32 v184, v128, v129
	v_cvt_pk_bf16_f32 v185, v130, v131
	v_cvt_pk_bf16_f32 v186, v132, v133
	v_cvt_pk_bf16_f32 v187, v134, v135
	s_add_u32 s2, s24, 0x180000
	s_addc_u32 s3, s25, 0
	global_store_dwordx4 v19, v[184:187], s[2:3]
	v_mul_f32_e32 v161, v136, v136
	v_fmac_f32_e32 v161, v137, v137
	v_fmac_f32_e32 v161, v138, v138
	v_fmac_f32_e32 v161, v139, v139
	v_fmac_f32_e32 v161, v140, v140
	v_fmac_f32_e32 v161, v141, v141
	v_fmac_f32_e32 v161, v142, v142
	v_fmac_f32_e32 v161, v143, v143
	v_cvt_pk_bf16_f32 v188, v136, v137
	v_cvt_pk_bf16_f32 v189, v138, v139
	v_cvt_pk_bf16_f32 v190, v140, v141
	v_cvt_pk_bf16_f32 v191, v142, v143
	s_add_u32 s2, s24, 0x1a0000
	s_addc_u32 s3, s25, 0
	global_store_dwordx4 v19, v[188:191], s[2:3]
	v_mul_f32_e32 v162, v144, v144
	v_fmac_f32_e32 v162, v145, v145
	v_fmac_f32_e32 v162, v146, v146
	v_fmac_f32_e32 v162, v147, v147
	v_fmac_f32_e32 v162, v148, v148
	v_fmac_f32_e32 v162, v149, v149
	v_fmac_f32_e32 v162, v150, v150
	v_fmac_f32_e32 v162, v151, v151
	v_cvt_pk_bf16_f32 v192, v144, v145
	v_cvt_pk_bf16_f32 v193, v146, v147
	v_cvt_pk_bf16_f32 v194, v148, v149
	v_cvt_pk_bf16_f32 v195, v150, v151
	s_add_u32 s2, s24, 0x1c0000
	s_addc_u32 s3, s25, 0
	global_store_dwordx4 v19, v[192:195], s[2:3]
	v_mul_f32_e32 v163, v152, v152
	v_fmac_f32_e32 v163, v153, v153
	v_fmac_f32_e32 v163, v154, v154
	v_fmac_f32_e32 v163, v155, v155
	v_fmac_f32_e32 v163, v156, v156
	v_fmac_f32_e32 v163, v157, v157
	v_fmac_f32_e32 v163, v158, v158
	v_fmac_f32_e32 v163, v159, v159
	v_cvt_pk_bf16_f32 v196, v152, v153
	v_cvt_pk_bf16_f32 v197, v154, v155
	v_cvt_pk_bf16_f32 v198, v156, v157
	v_cvt_pk_bf16_f32 v199, v158, v159
	s_add_u32 s2, s24, 0x1e0000
	s_addc_u32 s3, s25, 0
	global_store_dwordx4 v19, v[196:199], s[2:3]
	ds_bpermute_b32 v168, v23, v160
	ds_bpermute_b32 v169, v23, v161
	ds_bpermute_b32 v170, v23, v162
	ds_bpermute_b32 v171, v23, v163
	s_waitcnt lgkmcnt(0)
	v_add_f32_e32 v160, v160, v168
	v_add_f32_e32 v161, v161, v169
	v_add_f32_e32 v162, v162, v170
	v_add_f32_e32 v163, v163, v171
	ds_bpermute_b32 v168, v24, v160
	ds_bpermute_b32 v169, v24, v161
	ds_bpermute_b32 v170, v24, v162
	ds_bpermute_b32 v171, v24, v163
	s_waitcnt lgkmcnt(0)
	v_add_f32_e32 v160, v160, v168
	v_add_f32_e32 v161, v161, v169
	v_add_f32_e32 v162, v162, v170
	v_add_f32_e32 v163, v163, v171
	s_mov_b64 exec, 0xffff
	ds_write_b32 v25, v160
	ds_write_b32 v25, v161 offset:64
	ds_write_b32 v25, v162 offset:128
	ds_write_b32 v25, v163 offset:192
	s_mov_b64 exec, -1
	s_waitcnt lgkmcnt(0)
	s_waitcnt vmcnt(16)
	s_barrier
	s_cmp_lg_u32 s92, 0
	s_cbranch_scc1 .Lfftb_nored3
	ds_read_b32 v168, v26
	ds_read_b32 v169, v26 offset:256
	ds_read_b32 v170, v26 offset:512
	ds_read_b32 v171, v26 offset:768
	ds_read_b32 v172, v26 offset:1024
	ds_read_b32 v173, v26 offset:1280
	ds_read_b32 v174, v26 offset:1536
	ds_read_b32 v175, v26 offset:1792
	s_waitcnt lgkmcnt(0)
	v_add_f32_e32 v168, v168, v169
	v_add_f32_e32 v170, v170, v171
	v_add_f32_e32 v172, v172, v173
	v_add_f32_e32 v174, v174, v175
	v_add_f32_e32 v168, v168, v170
	v_add_f32_e32 v172, v172, v174
	v_add_f32_e32 v168, v168, v172
	s_add_u32 s2, s28, 0x18000
	s_addc_u32 s3, s29, 0
	global_atomic_add_f32 v27, v168, s[2:3]
.Lfftb_nored3:
	ds_read_b128 v[96:99], v15
	ds_read_b128 v[100:103], v15 offset:1024
	ds_read_b128 v[104:107], v15 offset:2048
	ds_read_b128 v[108:111], v15 offset:3072
	s_waitcnt lgkmcnt(0)
	s_setprio 1
	v_mfma_f32_16x16x32_bf16 v[128:131], v[96:99], v[32:35], 0
	v_mfma_f32_16x16x32_bf16 v[132:135], v[104:107], v[32:35], 0
	v_mfma_f32_16x16x32_bf16 v[136:139], v[96:99], v[40:43], 0
	v_mfma_f32_16x16x32_bf16 v[140:143], v[104:107], v[40:43], 0
	v_mfma_f32_16x16x32_bf16 v[144:147], v[96:99], v[48:51], 0
	v_mfma_f32_16x16x32_bf16 v[148:151], v[104:107], v[48:51], 0
	v_mfma_f32_16x16x32_bf16 v[152:155], v[96:99], v[56:59], 0
	v_mfma_f32_16x16x32_bf16 v[156:159], v[104:107], v[56:59], 0
	v_mfma_f32_16x16x32_bf16 v[128:131], v[100:103], v[36:39], v[128:131]
	v_mfma_f32_16x16x32_bf16 v[132:135], v[108:111], v[36:39], v[132:135]
	v_mfma_f32_16x16x32_bf16 v[136:139], v[100:103], v[44:47], v[136:139]
	v_mfma_f32_16x16x32_bf16 v[140:143], v[108:111], v[44:47], v[140:143]
	v_mfma_f32_16x16x32_bf16 v[144:147], v[100:103], v[52:55], v[144:147]
	v_mfma_f32_16x16x32_bf16 v[148:151], v[108:111], v[52:55], v[148:151]
	v_mfma_f32_16x16x32_bf16 v[152:155], v[100:103], v[60:63], v[152:155]
	v_mfma_f32_16x16x32_bf16 v[156:159], v[108:111], v[60:63], v[156:159]
	s_setprio 0
	s_add_u32 s0, s20, 0x5000080
	s_addc_u32 s1, s21, 0
	s_add_i32 m0, s38, 0x18000
	s_nop 0
	global_load_lds_dwordx4 v10, s[0:1]
	s_add_i32 m0, s38, 0x18400
	s_nop 0
	global_load_lds_dwordx4 v11, s[0:1]
	s_add_i32 m0, s38, 0x18800
	s_nop 0
	global_load_lds_dwordx4 v12, s[0:1]
	s_add_i32 m0, s38, 0x18c00
	s_nop 0
	global_load_lds_dwordx4 v13, s[0:1]
	s_add_u32 s0, s36, 0x0
	s_addc_u32 s1, s37, 0
	s_add_i32 m0, s39, 0x0
	s_nop 0
	global_load_lds_dwordx4 v14, s[0:1]
	s_add_u32 s0, s36, 0x80
	s_addc_u32 s1, s37, 0
	s_add_i32 m0, s39, 0x2000
	s_nop 0
	global_load_lds_dwordx4 v14, s[0:1]
	s_waitcnt vmcnt(14)
	s_barrier
	ds_read_b128 v[96:99], v16
	ds_read_b128 v[100:103], v16 offset:1024
	ds_read_b128 v[104:107], v16 offset:2048
	ds_read_b128 v[108:111], v16 offset:3072
	s_waitcnt lgkmcnt(0)
	s_setprio 1
	v_mfma_f32_16x16x32_bf16 v[128:131], v[96:99], v[64:67], v[128:131]
	v_mfma_f32_16x16x32_bf16 v[132:135], v[104:107], v[64:67], v[132:135]
	v_mfma_f32_16x16x32_bf16 v[136:139], v[96:99], v[72:75], v[136:139]
	v_mfma_f32_16x16x32_bf16 v[140:143], v[104:107], v[72:75], v[140:143]
	v_mfma_f32_16x16x32_bf16 v[144:147], v[96:99], v[80:83], v[144:147]
	v_mfma_f32_16x16x32_bf16 v[148:151], v[104:107], v[80:83], v[148:151]
	v_mfma_f32_16x16x32_bf16 v[152:155], v[96:99], v[88:91], v[152:155]
	v_mfma_f32_16x16x32_bf16 v[156:159], v[104:107], v[88:91], v[156:159]
	v_mfma_f32_16x16x32_bf16 v[128:131], v[100:103], v[68:71], v[128:131]
	v_mfma_f32_16x16x32_bf16 v[132:135], v[108:111], v[68:71], v[132:135]
	v_mfma_f32_16x16x32_bf16 v[136:139], v[100:103], v[76:79], v[136:139]
	v_mfma_f32_16x16x32_bf16 v[140:143], v[108:111], v[76:79], v[140:143]
	v_mfma_f32_16x16x32_bf16 v[144:147], v[100:103], v[84:87], v[144:147]
	v_mfma_f32_16x16x32_bf16 v[148:151], v[108:111], v[84:87], v[148:151]
	v_mfma_f32_16x16x32_bf16 v[152:155], v[100:103], v[92:95], v[152:155]
	v_mfma_f32_16x16x32_bf16 v[156:159], v[108:111], v[92:95], v[156:159]
	s_setprio 0
	s_add_u32 s0, s20, 0x6000000
	s_addc_u32 s1, s21, 0
	s_add_i32 m0, s38, 0x0
	s_nop 0
	global_load_lds_dwordx4 v10, s[0:1]
	s_add_i32 m0, s38, 0x400
	s_nop 0
	global_load_lds_dwordx4 v11, s[0:1]
	s_add_i32 m0, s38, 0x800
	s_nop 0
	global_load_lds_dwordx4 v12, s[0:1]
	s_add_i32 m0, s38, 0xc00
	s_nop 0
	global_load_lds_dwordx4 v13, s[0:1]
	s_nop 7
	v_mul_f32_e32 v160, v128, v128
	v_fmac_f32_e32 v160, v129, v129
	v_fmac_f32_e32 v160, v130, v130
	v_fmac_f32_e32 v160, v131, v131
	v_fmac_f32_e32 v160, v132, v132
	v_fmac_f32_e32 v160, v133, v133
	v_fmac_f32_e32 v160, v134, v134
	v_fmac_f32_e32 v160, v135, v135
	v_cvt_pk_bf16_f32 v184, v128, v129
	v_cvt_pk_bf16_f32 v185, v130, v131
	v_cvt_pk_bf16_f32 v186, v132, v133
	v_cvt_pk_bf16_f32 v187, v134, v135
	s_add_u32 s2, s24, 0x200000
	s_addc_u32 s3, s25, 0
	global_store_dwordx4 v19, v[184:187], s[2:3]
	v_mul_f32_e32 v161, v136, v136
	v_fmac_f32_e32 v161, v137, v137
	v_fmac_f32_e32 v161, v138, v138
	v_fmac_f32_e32 v161, v139, v139
	v_fmac_f32_e32 v161, v140, v140
	v_fmac_f32_e32 v161, v141, v141
	v_fmac_f32_e32 v161, v142, v142
	v_fmac_f32_e32 v161, v143, v143
	v_cvt_pk_bf16_f32 v188, v136, v137
	v_cvt_pk_bf16_f32 v189, v138, v139
	v_cvt_pk_bf16_f32 v190, v140, v141
	v_cvt_pk_bf16_f32 v191, v142, v143
	s_add_u32 s2, s24, 0x220000
	s_addc_u32 s3, s25, 0
	global_store_dwordx4 v19, v[188:191], s[2:3]
	v_mul_f32_e32 v162, v144, v144
	v_fmac_f32_e32 v162, v145, v145
	v_fmac_f32_e32 v162, v146, v146
	v_fmac_f32_e32 v162, v147, v147
	v_fmac_f32_e32 v162, v148, v148
	v_fmac_f32_e32 v162, v149, v149
	v_fmac_f32_e32 v162, v150, v150
	v_fmac_f32_e32 v162, v151, v151
	v_cvt_pk_bf16_f32 v192, v144, v145
	v_cvt_pk_bf16_f32 v193, v146, v147
	v_cvt_pk_bf16_f32 v194, v148, v149
	v_cvt_pk_bf16_f32 v195, v150, v151
	s_add_u32 s2, s24, 0x240000
	s_addc_u32 s3, s25, 0
	global_store_dwordx4 v19, v[192:195], s[2:3]
	v_mul_f32_e32 v163, v152, v152
	v_fmac_f32_e32 v163, v153, v153
	v_fmac_f32_e32 v163, v154, v154
	v_fmac_f32_e32 v163, v155, v155
	v_fmac_f32_e32 v163, v156, v156
	v_fmac_f32_e32 v163, v157, v157
	v_fmac_f32_e32 v163, v158, v158
	v_fmac_f32_e32 v163, v159, v159
	v_cvt_pk_bf16_f32 v196, v152, v153
	v_cvt_pk_bf16_f32 v197, v154, v155
	v_cvt_pk_bf16_f32 v198, v156, v157
	v_cvt_pk_bf16_f32 v199, v158, v159
	s_add_u32 s2, s24, 0x260000
	s_addc_u32 s3, s25, 0
	global_store_dwordx4 v19, v[196:199], s[2:3]
	ds_bpermute_b32 v168, v23, v160
	ds_bpermute_b32 v169, v23, v161
	ds_bpermute_b32 v170, v23, v162
	ds_bpermute_b32 v171, v23, v163
	s_waitcnt lgkmcnt(0)
	v_add_f32_e32 v160, v160, v168
	v_add_f32_e32 v161, v161, v169
	v_add_f32_e32 v162, v162, v170
	v_add_f32_e32 v163, v163, v171
	ds_bpermute_b32 v168, v24, v160
	ds_bpermute_b32 v169, v24, v161
	ds_bpermute_b32 v170, v24, v162
	ds_bpermute_b32 v171, v24, v163
	s_waitcnt lgkmcnt(0)
	v_add_f32_e32 v160, v160, v168
	v_add_f32_e32 v161, v161, v169
	v_add_f32_e32 v162, v162, v170
	v_add_f32_e32 v163, v163, v171
	s_mov_b64 exec, 0xffff
	ds_write_b32 v25, v160
	ds_write_b32 v25, v161 offset:64
	ds_write_b32 v25, v162 offset:128
	ds_write_b32 v25, v163 offset:192
	s_mov_b64 exec, -1
	s_waitcnt lgkmcnt(0)
	s_waitcnt vmcnt(18)
	s_barrier
	s_cmp_lg_u32 s92, 0
	s_cbranch_scc1 .Lfftb_nored4
	ds_read_b32 v168, v26
	ds_read_b32 v169, v26 offset:256
	ds_read_b32 v170, v26 offset:512
	ds_read_b32 v171, v26 offset:768
	ds_read_b32 v172, v26 offset:1024
	ds_read_b32 v173, v26 offset:1280
	ds_read_b32 v174, v26 offset:1536
	ds_read_b32 v175, v26 offset:1792
	s_waitcnt lgkmcnt(0)
	v_add_f32_e32 v168, v168, v169
	v_add_f32_e32 v170, v170, v171
	v_add_f32_e32 v172, v172, v173
	v_add_f32_e32 v174, v174, v175
	v_add_f32_e32 v168, v168, v170
	v_add_f32_e32 v172, v172, v174
	v_add_f32_e32 v168, v168, v172
	s_add_u32 s2, s28, 0x20000
	s_addc_u32 s3, s29, 0
	global_atomic_add_f32 v27, v168, s[2:3]
.Lfftb_nored4:
	ds_read_b128 v[96:99], v17
	ds_read_b128 v[100:103], v17 offset:1024
	ds_read_b128 v[104:107], v17 offset:2048
	ds_read_b128 v[108:111], v17 offset:3072
	s_waitcnt lgkmcnt(0)
	s_setprio 1
	v_mfma_f32_16x16x32_bf16 v[128:131], v[96:99], v[32:35], 0
	v_mfma_f32_16x16x32_bf16 v[132:135], v[104:107], v[32:35], 0
	v_mfma_f32_16x16x32_bf16 v[136:139], v[96:99], v[40:43], 0
	v_mfma_f32_16x16x32_bf16 v[140:143], v[104:107], v[40:43], 0
	v_mfma_f32_16x16x32_bf16 v[144:147], v[96:99], v[48:51], 0
	v_mfma_f32_16x16x32_bf16 v[148:151], v[104:107], v[48:51], 0
	v_mfma_f32_16x16x32_bf16 v[152:155], v[96:99], v[56:59], 0
	v_mfma_f32_16x16x32_bf16 v[156:159], v[104:107], v[56:59], 0
	v_mfma_f32_16x16x32_bf16 v[128:131], v[100:103], v[36:39], v[128:131]
	v_mfma_f32_16x16x32_bf16 v[132:135], v[108:111], v[36:39], v[132:135]
	v_mfma_f32_16x16x32_bf16 v[136:139], v[100:103], v[44:47], v[136:139]
	v_mfma_f32_16x16x32_bf16 v[140:143], v[108:111], v[44:47], v[140:143]
	v_mfma_f32_16x16x32_bf16 v[144:147], v[100:103], v[52:55], v[144:147]
	v_mfma_f32_16x16x32_bf16 v[148:151], v[108:111], v[52:55], v[148:151]
	v_mfma_f32_16x16x32_bf16 v[152:155], v[100:103], v[60:63], v[152:155]
	v_mfma_f32_16x16x32_bf16 v[156:159], v[108:111], v[60:63], v[156:159]
	s_setprio 0
	s_add_u32 s0, s20, 0x6000080
	s_addc_u32 s1, s21, 0
	s_add_i32 m0, s38, 0x8000
	s_nop 0
	global_load_lds_dwordx4 v10, s[0:1]
	s_add_i32 m0, s38, 0x8400
	s_nop 0
	global_load_lds_dwordx4 v11, s[0:1]
	s_add_i32 m0, s38, 0x8800
	s_nop 0
	global_load_lds_dwordx4 v12, s[0:1]
	s_add_i32 m0, s38, 0x8c00
	s_nop 0
	global_load_lds_dwordx4 v13, s[0:1]
	s_waitcnt vmcnt(14)
	s_barrier
	ds_read_b128 v[96:99], v29
	ds_read_b128 v[100:103], v29 offset:1024
	ds_read_b128 v[104:107], v29 offset:2048
	ds_read_b128 v[108:111], v29 offset:3072
	s_waitcnt lgkmcnt(0)
	s_setprio 1
	v_mfma_f32_16x16x32_bf16 v[128:131], v[96:99], v[64:67], v[128:131]
	v_mfma_f32_16x16x32_bf16 v[132:135], v[104:107], v[64:67], v[132:135]
	v_mfma_f32_16x16x32_bf16 v[136:139], v[96:99], v[72:75], v[136:139]
	v_mfma_f32_16x16x32_bf16 v[140:143], v[104:107], v[72:75], v[140:143]
	v_mfma_f32_16x16x32_bf16 v[144:147], v[96:99], v[80:83], v[144:147]
	v_mfma_f32_16x16x32_bf16 v[148:151], v[104:107], v[80:83], v[148:151]
	v_mfma_f32_16x16x32_bf16 v[152:155], v[96:99], v[88:91], v[152:155]
	v_mfma_f32_16x16x32_bf16 v[156:159], v[104:107], v[88:91], v[156:159]
	v_mfma_f32_16x16x32_bf16 v[128:131], v[100:103], v[68:71], v[128:131]
	v_mfma_f32_16x16x32_bf16 v[132:135], v[108:111], v[68:71], v[132:135]
	v_mfma_f32_16x16x32_bf16 v[136:139], v[100:103], v[76:79], v[136:139]
	v_mfma_f32_16x16x32_bf16 v[140:143], v[108:111], v[76:79], v[140:143]
	v_mfma_f32_16x16x32_bf16 v[144:147], v[100:103], v[84:87], v[144:147]
	v_mfma_f32_16x16x32_bf16 v[148:151], v[108:111], v[84:87], v[148:151]
	v_mfma_f32_16x16x32_bf16 v[152:155], v[100:103], v[92:95], v[152:155]
	v_mfma_f32_16x16x32_bf16 v[156:159], v[108:111], v[92:95], v[156:159]
	s_setprio 0
	s_add_u32 s0, s20, 0x7000000
	s_addc_u32 s1, s21, 0
	s_add_i32 m0, s38, 0x10000
	s_nop 0
	global_load_lds_dwordx4 v10, s[0:1]
	s_add_i32 m0, s38, 0x10400
	s_nop 0
	global_load_lds_dwordx4 v11, s[0:1]
	s_add_i32 m0, s38, 0x10800
	s_nop 0
	global_load_lds_dwordx4 v12, s[0:1]
	s_add_i32 m0, s38, 0x10c00
	s_nop 0
	global_load_lds_dwordx4 v13, s[0:1]
	s_nop 7
	v_mul_f32_e32 v160, v128, v128
	v_fmac_f32_e32 v160, v129, v129
	v_fmac_f32_e32 v160, v130, v130
	v_fmac_f32_e32 v160, v131, v131
	v_fmac_f32_e32 v160, v132, v132
	v_fmac_f32_e32 v160, v133, v133
	v_fmac_f32_e32 v160, v134, v134
	v_fmac_f32_e32 v160, v135, v135
	v_cvt_pk_bf16_f32 v184, v128, v129
	v_cvt_pk_bf16_f32 v185, v130, v131
	v_cvt_pk_bf16_f32 v186, v132, v133
	v_cvt_pk_bf16_f32 v187, v134, v135
	s_add_u32 s2, s24, 0x280000
	s_addc_u32 s3, s25, 0
	global_store_dwordx4 v19, v[184:187], s[2:3]
	v_mul_f32_e32 v161, v136, v136
	v_fmac_f32_e32 v161, v137, v137
	v_fmac_f32_e32 v161, v138, v138
	v_fmac_f32_e32 v161, v139, v139
	v_fmac_f32_e32 v161, v140, v140
	v_fmac_f32_e32 v161, v141, v141
	v_fmac_f32_e32 v161, v142, v142
	v_fmac_f32_e32 v161, v143, v143
	v_cvt_pk_bf16_f32 v188, v136, v137
	v_cvt_pk_bf16_f32 v189, v138, v139
	v_cvt_pk_bf16_f32 v190, v140, v141
	v_cvt_pk_bf16_f32 v191, v142, v143
	s_add_u32 s2, s24, 0x2a0000
	s_addc_u32 s3, s25, 0
	global_store_dwordx4 v19, v[188:191], s[2:3]
	v_mul_f32_e32 v162, v144, v144
	v_fmac_f32_e32 v162, v145, v145
	v_fmac_f32_e32 v162, v146, v146
	v_fmac_f32_e32 v162, v147, v147
	v_fmac_f32_e32 v162, v148, v148
	v_fmac_f32_e32 v162, v149, v149
	v_fmac_f32_e32 v162, v150, v150
	v_fmac_f32_e32 v162, v151, v151
	v_cvt_pk_bf16_f32 v192, v144, v145
	v_cvt_pk_bf16_f32 v193, v146, v147
	v_cvt_pk_bf16_f32 v194, v148, v149
	v_cvt_pk_bf16_f32 v195, v150, v151
	s_add_u32 s2, s24, 0x2c0000
	s_addc_u32 s3, s25, 0
	global_store_dwordx4 v19, v[192:195], s[2:3]
	v_mul_f32_e32 v163, v152, v152
	v_fmac_f32_e32 v163, v153, v153
	v_fmac_f32_e32 v163, v154, v154
	v_fmac_f32_e32 v163, v155, v155
	v_fmac_f32_e32 v163, v156, v156
	v_fmac_f32_e32 v163, v157, v157
	v_fmac_f32_e32 v163, v158, v158
	v_fmac_f32_e32 v163, v159, v159
	v_cvt_pk_bf16_f32 v196, v152, v153
	v_cvt_pk_bf16_f32 v197, v154, v155
	v_cvt_pk_bf16_f32 v198, v156, v157
	v_cvt_pk_bf16_f32 v199, v158, v159
	s_add_u32 s2, s24, 0x2e0000
	s_addc_u32 s3, s25, 0
	global_store_dwordx4 v19, v[196:199], s[2:3]
	ds_bpermute_b32 v168, v23, v160
	ds_bpermute_b32 v169, v23, v161
	ds_bpermute_b32 v170, v23, v162
	ds_bpermute_b32 v171, v23, v163
	s_waitcnt lgkmcnt(0)
	v_add_f32_e32 v160, v160, v168
	v_add_f32_e32 v161, v161, v169
	v_add_f32_e32 v162, v162, v170
	v_add_f32_e32 v163, v163, v171
	ds_bpermute_b32 v168, v24, v160
	ds_bpermute_b32 v169, v24, v161
	ds_bpermute_b32 v170, v24, v162
	ds_bpermute_b32 v171, v24, v163
	s_waitcnt lgkmcnt(0)
	v_add_f32_e32 v160, v160, v168
	v_add_f32_e32 v161, v161, v169
	v_add_f32_e32 v162, v162, v170
	v_add_f32_e32 v163, v163, v171
	s_mov_b64 exec, 0xffff
	ds_write_b32 v25, v160
	ds_write_b32 v25, v161 offset:64
	ds_write_b32 v25, v162 offset:128
	ds_write_b32 v25, v163 offset:192
	s_mov_b64 exec, -1
	s_waitcnt lgkmcnt(0)
	s_waitcnt vmcnt(16)
	s_barrier
	s_cmp_lg_u32 s92, 0
	s_cbranch_scc1 .Lfftb_nored5
	ds_read_b32 v168, v26
	ds_read_b32 v169, v26 offset:256
	ds_read_b32 v170, v26 offset:512
	ds_read_b32 v171, v26 offset:768
	ds_read_b32 v172, v26 offset:1024
	ds_read_b32 v173, v26 offset:1280
	ds_read_b32 v174, v26 offset:1536
	ds_read_b32 v175, v26 offset:1792
	s_waitcnt lgkmcnt(0)
	v_add_f32_e32 v168, v168, v169
	v_add_f32_e32 v170, v170, v171
	v_add_f32_e32 v172, v172, v173
	v_add_f32_e32 v174, v174, v175
	v_add_f32_e32 v168, v168, v170
	v_add_f32_e32 v172, v172, v174
	v_add_f32_e32 v168, v168, v172
	s_add_u32 s2, s28, 0x28000
	s_addc_u32 s3, s29, 0
	global_atomic_add_f32 v27, v168, s[2:3]
.Lfftb_nored5:
	ds_read_b128 v[96:99], v15
	ds_read_b128 v[100:103], v15 offset:1024
	ds_read_b128 v[104:107], v15 offset:2048
	ds_read_b128 v[108:111], v15 offset:3072
	s_waitcnt lgkmcnt(0)
	s_setprio 1
	v_mfma_f32_16x16x32_bf16 v[128:131], v[96:99], v[32:35], 0
	v_mfma_f32_16x16x32_bf16 v[132:135], v[104:107], v[32:35], 0
	v_mfma_f32_16x16x32_bf16 v[136:139], v[96:99], v[40:43], 0
	v_mfma_f32_16x16x32_bf16 v[140:143], v[104:107], v[40:43], 0
	v_mfma_f32_16x16x32_bf16 v[144:147], v[96:99], v[48:51], 0
	v_mfma_f32_16x16x32_bf16 v[148:151], v[104:107], v[48:51], 0
	v_mfma_f32_16x16x32_bf16 v[152:155], v[96:99], v[56:59], 0
	v_mfma_f32_16x16x32_bf16 v[156:159], v[104:107], v[56:59], 0
	v_mfma_f32_16x16x32_bf16 v[128:131], v[100:103], v[36:39], v[128:131]
	v_mfma_f32_16x16x32_bf16 v[132:135], v[108:111], v[36:39], v[132:135]
	v_mfma_f32_16x16x32_bf16 v[136:139], v[100:103], v[44:47], v[136:139]
	v_mfma_f32_16x16x32_bf16 v[140:143], v[108:111], v[44:47], v[140:143]
	v_mfma_f32_16x16x32_bf16 v[144:147], v[100:103], v[52:55], v[144:147]
	v_mfma_f32_16x16x32_bf16 v[148:151], v[108:111], v[52:55], v[148:151]
	v_mfma_f32_16x16x32_bf16 v[152:155], v[100:103], v[60:63], v[152:155]
	v_mfma_f32_16x16x32_bf16 v[156:159], v[108:111], v[60:63], v[156:159]
	s_setprio 0
	s_add_u32 s0, s20, 0x7000080
	s_addc_u32 s1, s21, 0
	s_add_i32 m0, s38, 0x18000
	s_nop 0
	global_load_lds_dwordx4 v10, s[0:1]
	s_add_i32 m0, s38, 0x18400
	s_nop 0
	global_load_lds_dwordx4 v11, s[0:1]
	s_add_i32 m0, s38, 0x18800
	s_nop 0
	global_load_lds_dwordx4 v12, s[0:1]
	s_add_i32 m0, s38, 0x18c00
	s_nop 0
	global_load_lds_dwordx4 v13, s[0:1]
	s_waitcnt vmcnt(12)
	s_barrier
	ds_read_b128 v[96:99], v16
	ds_read_b128 v[100:103], v16 offset:1024
	ds_read_b128 v[104:107], v16 offset:2048
	ds_read_b128 v[108:111], v16 offset:3072
	s_waitcnt lgkmcnt(0)
	s_setprio 1
	v_mfma_f32_16x16x32_bf16 v[128:131], v[96:99], v[64:67], v[128:131]
	v_mfma_f32_16x16x32_bf16 v[132:135], v[104:107], v[64:67], v[132:135]
	v_mfma_f32_16x16x32_bf16 v[136:139], v[96:99], v[72:75], v[136:139]
	v_mfma_f32_16x16x32_bf16 v[140:143], v[104:107], v[72:75], v[140:143]
	v_mfma_f32_16x16x32_bf16 v[144:147], v[96:99], v[80:83], v[144:147]
	v_mfma_f32_16x16x32_bf16 v[148:151], v[104:107], v[80:83], v[148:151]
	v_mfma_f32_16x16x32_bf16 v[152:155], v[96:99], v[88:91], v[152:155]
	v_mfma_f32_16x16x32_bf16 v[156:159], v[104:107], v[88:91], v[156:159]
	v_mfma_f32_16x16x32_bf16 v[128:131], v[100:103], v[68:71], v[128:131]
	v_mfma_f32_16x16x32_bf16 v[132:135], v[108:111], v[68:71], v[132:135]
	v_mfma_f32_16x16x32_bf16 v[136:139], v[100:103], v[76:79], v[136:139]
	v_mfma_f32_16x16x32_bf16 v[140:143], v[108:111], v[76:79], v[140:143]
	v_mfma_f32_16x16x32_bf16 v[144:147], v[100:103], v[84:87], v[144:147]
	v_mfma_f32_16x16x32_bf16 v[148:151], v[108:111], v[84:87], v[148:151]
	v_mfma_f32_16x16x32_bf16 v[152:155], v[100:103], v[92:95], v[152:155]
	v_mfma_f32_16x16x32_bf16 v[156:159], v[108:111], v[92:95], v[156:159]
	s_setprio 0
	s_add_u32 s0, s22, 0x0
	s_addc_u32 s1, s23, 0
	s_add_i32 m0, s38, 0x0
	s_nop 0
	global_load_lds_dwordx4 v10, s[0:1]
	s_add_i32 m0, s38, 0x400
	s_nop 0
	global_load_lds_dwordx4 v11, s[0:1]
	s_add_i32 m0, s38, 0x800
	s_nop 0
	global_load_lds_dwordx4 v12, s[0:1]
	s_add_i32 m0, s38, 0xc00
	s_nop 0
	global_load_lds_dwordx4 v13, s[0:1]
	s_nop 7
	v_mul_f32_e32 v160, v128, v128
	v_fmac_f32_e32 v160, v129, v129
	v_fmac_f32_e32 v160, v130, v130
	v_fmac_f32_e32 v160, v131, v131
	v_fmac_f32_e32 v160, v132, v132
	v_fmac_f32_e32 v160, v133, v133
	v_fmac_f32_e32 v160, v134, v134
	v_fmac_f32_e32 v160, v135, v135
	v_cvt_pk_bf16_f32 v184, v128, v129
	v_cvt_pk_bf16_f32 v185, v130, v131
	v_cvt_pk_bf16_f32 v186, v132, v133
	v_cvt_pk_bf16_f32 v187, v134, v135
	s_add_u32 s2, s24, 0x300000
	s_addc_u32 s3, s25, 0
	global_store_dwordx4 v19, v[184:187], s[2:3]
	v_mul_f32_e32 v161, v136, v136
	v_fmac_f32_e32 v161, v137, v137
	v_fmac_f32_e32 v161, v138, v138
	v_fmac_f32_e32 v161, v139, v139
	v_fmac_f32_e32 v161, v140, v140
	v_fmac_f32_e32 v161, v141, v141
	v_fmac_f32_e32 v161, v142, v142
	v_fmac_f32_e32 v161, v143, v143
	v_cvt_pk_bf16_f32 v188, v136, v137
	v_cvt_pk_bf16_f32 v189, v138, v139
	v_cvt_pk_bf16_f32 v190, v140, v141
	v_cvt_pk_bf16_f32 v191, v142, v143
	s_add_u32 s2, s24, 0x320000
	s_addc_u32 s3, s25, 0
	global_store_dwordx4 v19, v[188:191], s[2:3]
	v_mul_f32_e32 v162, v144, v144
	v_fmac_f32_e32 v162, v145, v145
	v_fmac_f32_e32 v162, v146, v146
	v_fmac_f32_e32 v162, v147, v147
	v_fmac_f32_e32 v162, v148, v148
	v_fmac_f32_e32 v162, v149, v149
	v_fmac_f32_e32 v162, v150, v150
	v_fmac_f32_e32 v162, v151, v151
	v_cvt_pk_bf16_f32 v192, v144, v145
	v_cvt_pk_bf16_f32 v193, v146, v147
	v_cvt_pk_bf16_f32 v194, v148, v149
	v_cvt_pk_bf16_f32 v195, v150, v151
	s_add_u32 s2, s24, 0x340000
	s_addc_u32 s3, s25, 0
	global_store_dwordx4 v19, v[192:195], s[2:3]
	v_mul_f32_e32 v163, v152, v152
	v_fmac_f32_e32 v163, v153, v153
	v_fmac_f32_e32 v163, v154, v154
	v_fmac_f32_e32 v163, v155, v155
	v_fmac_f32_e32 v163, v156, v156
	v_fmac_f32_e32 v163, v157, v157
	v_fmac_f32_e32 v163, v158, v158
	v_fmac_f32_e32 v163, v159, v159
	v_cvt_pk_bf16_f32 v196, v152, v153
	v_cvt_pk_bf16_f32 v197, v154, v155
	v_cvt_pk_bf16_f32 v198, v156, v157
	v_cvt_pk_bf16_f32 v199, v158, v159
	s_add_u32 s2, s24, 0x360000
	s_addc_u32 s3, s25, 0
	global_store_dwordx4 v19, v[196:199], s[2:3]
	ds_bpermute_b32 v168, v23, v160
	ds_bpermute_b32 v169, v23, v161
	ds_bpermute_b32 v170, v23, v162
	ds_bpermute_b32 v171, v23, v163
	s_waitcnt lgkmcnt(0)
	v_add_f32_e32 v160, v160, v168
	v_add_f32_e32 v161, v161, v169
	v_add_f32_e32 v162, v162, v170
	v_add_f32_e32 v163, v163, v171
	ds_bpermute_b32 v168, v24, v160
	ds_bpermute_b32 v169, v24, v161
	ds_bpermute_b32 v170, v24, v162
	ds_bpermute_b32 v171, v24, v163
	s_waitcnt lgkmcnt(0)
	v_add_f32_e32 v160, v160, v168
	v_add_f32_e32 v161, v161, v169
	v_add_f32_e32 v162, v162, v170
	v_add_f32_e32 v163, v163, v171
	s_mov_b64 exec, 0xffff
	ds_write_b32 v25, v160
	ds_write_b32 v25, v161 offset:64
	ds_write_b32 v25, v162 offset:128
	ds_write_b32 v25, v163 offset:192
	s_mov_b64 exec, -1
	s_waitcnt lgkmcnt(0)
	s_waitcnt vmcnt(16)
	s_barrier
	s_cmp_lg_u32 s92, 0
	s_cbranch_scc1 .Lfftb_nored6
	ds_read_b32 v168, v26
	ds_read_b32 v169, v26 offset:256
	ds_read_b32 v170, v26 offset:512
	ds_read_b32 v171, v26 offset:768
	ds_read_b32 v172, v26 offset:1024
	ds_read_b32 v173, v26 offset:1280
	ds_read_b32 v174, v26 offset:1536
	ds_read_b32 v175, v26 offset:1792
	s_waitcnt lgkmcnt(0)
	v_add_f32_e32 v168, v168, v169
	v_add_f32_e32 v170, v170, v171
	v_add_f32_e32 v172, v172, v173
	v_add_f32_e32 v174, v174, v175
	v_add_f32_e32 v168, v168, v170
	v_add_f32_e32 v172, v172, v174
	v_add_f32_e32 v168, v168, v172
	s_add_u32 s2, s28, 0x30000
	s_addc_u32 s3, s29, 0
	global_atomic_add_f32 v27, v168, s[2:3]
.Lfftb_nored6:
	ds_read_b128 v[96:99], v17
	ds_read_b128 v[100:103], v17 offset:1024
	ds_read_b128 v[104:107], v17 offset:2048
	ds_read_b128 v[108:111], v17 offset:3072
	s_waitcnt lgkmcnt(0)
	s_setprio 1
	v_mfma_f32_16x16x32_bf16 v[128:131], v[96:99], v[32:35], 0
	v_mfma_f32_16x16x32_bf16 v[132:135], v[104:107], v[32:35], 0
	v_mfma_f32_16x16x32_bf16 v[136:139], v[96:99], v[40:43], 0
	v_mfma_f32_16x16x32_bf16 v[140:143], v[104:107], v[40:43], 0
	v_mfma_f32_16x16x32_bf16 v[144:147], v[96:99], v[48:51], 0
	v_mfma_f32_16x16x32_bf16 v[148:151], v[104:107], v[48:51], 0
	v_mfma_f32_16x16x32_bf16 v[152:155], v[96:99], v[56:59], 0
	v_mfma_f32_16x16x32_bf16 v[156:159], v[104:107], v[56:59], 0
	v_mfma_f32_16x16x32_bf16 v[128:131], v[100:103], v[36:39], v[128:131]
	v_mfma_f32_16x16x32_bf16 v[132:135], v[108:111], v[36:39], v[132:135]
	v_mfma_f32_16x16x32_bf16 v[136:139], v[100:103], v[44:47], v[136:139]
	v_mfma_f32_16x16x32_bf16 v[140:143], v[108:111], v[44:47], v[140:143]
	v_mfma_f32_16x16x32_bf16 v[144:147], v[100:103], v[52:55], v[144:147]
	v_mfma_f32_16x16x32_bf16 v[148:151], v[108:111], v[52:55], v[148:151]
	v_mfma_f32_16x16x32_bf16 v[152:155], v[100:103], v[60:63], v[152:155]
	v_mfma_f32_16x16x32_bf16 v[156:159], v[108:111], v[60:63], v[156:159]
	s_setprio 0
	s_add_u32 s0, s22, 0x80
	s_addc_u32 s1, s23, 0
	s_add_i32 m0, s38, 0x8000
	s_nop 0
	global_load_lds_dwordx4 v10, s[0:1]
	s_add_i32 m0, s38, 0x8400
	s_nop 0
	global_load_lds_dwordx4 v11, s[0:1]
	s_add_i32 m0, s38, 0x8800
	s_nop 0
	global_load_lds_dwordx4 v12, s[0:1]
	s_add_i32 m0, s38, 0x8c00
	s_nop 0
	global_load_lds_dwordx4 v13, s[0:1]
	s_waitcnt vmcnt(12)
	s_barrier
	ds_read_b128 v[96:99], v29
	ds_read_b128 v[100:103], v29 offset:1024
	ds_read_b128 v[104:107], v29 offset:2048
	ds_read_b128 v[108:111], v29 offset:3072
	s_waitcnt lgkmcnt(0)
	s_setprio 1
	v_mfma_f32_16x16x32_bf16 v[128:131], v[96:99], v[64:67], v[128:131]
	v_mfma_f32_16x16x32_bf16 v[132:135], v[104:107], v[64:67], v[132:135]
	v_mfma_f32_16x16x32_bf16 v[136:139], v[96:99], v[72:75], v[136:139]
	v_mfma_f32_16x16x32_bf16 v[140:143], v[104:107], v[72:75], v[140:143]
	v_mfma_f32_16x16x32_bf16 v[144:147], v[96:99], v[80:83], v[144:147]
	v_mfma_f32_16x16x32_bf16 v[148:151], v[104:107], v[80:83], v[148:151]
	v_mfma_f32_16x16x32_bf16 v[152:155], v[96:99], v[88:91], v[152:155]
	v_mfma_f32_16x16x32_bf16 v[156:159], v[104:107], v[88:91], v[156:159]
	v_mfma_f32_16x16x32_bf16 v[128:131], v[100:103], v[68:71], v[128:131]
	v_mfma_f32_16x16x32_bf16 v[132:135], v[108:111], v[68:71], v[132:135]
	v_mfma_f32_16x16x32_bf16 v[136:139], v[100:103], v[76:79], v[136:139]
	v_mfma_f32_16x16x32_bf16 v[140:143], v[108:111], v[76:79], v[140:143]
	v_mfma_f32_16x16x32_bf16 v[144:147], v[100:103], v[84:87], v[144:147]
	v_mfma_f32_16x16x32_bf16 v[148:151], v[108:111], v[84:87], v[148:151]
	v_mfma_f32_16x16x32_bf16 v[152:155], v[100:103], v[92:95], v[152:155]
	v_mfma_f32_16x16x32_bf16 v[156:159], v[108:111], v[92:95], v[156:159]
	s_setprio 0
	s_add_u32 s0, s22, 0x1000000
	s_addc_u32 s1, s23, 0
	s_add_i32 m0, s38, 0x10000
	s_nop 0
	global_load_lds_dwordx4 v10, s[0:1]
	s_add_i32 m0, s38, 0x10400
	s_nop 0
	global_load_lds_dwordx4 v11, s[0:1]
	s_add_i32 m0, s38, 0x10800
	s_nop 0
	global_load_lds_dwordx4 v12, s[0:1]
	s_add_i32 m0, s38, 0x10c00
	s_nop 0
	global_load_lds_dwordx4 v13, s[0:1]
	s_nop 7
	v_mul_f32_e32 v160, v128, v128
	v_fmac_f32_e32 v160, v129, v129
	v_fmac_f32_e32 v160, v130, v130
	v_fmac_f32_e32 v160, v131, v131
	v_fmac_f32_e32 v160, v132, v132
	v_fmac_f32_e32 v160, v133, v133
	v_fmac_f32_e32 v160, v134, v134
	v_fmac_f32_e32 v160, v135, v135
	v_cvt_pk_bf16_f32 v184, v128, v129
	v_cvt_pk_bf16_f32 v185, v130, v131
	v_cvt_pk_bf16_f32 v186, v132, v133
	v_cvt_pk_bf16_f32 v187, v134, v135
	s_add_u32 s2, s24, 0x380000
	s_addc_u32 s3, s25, 0
	global_store_dwordx4 v19, v[184:187], s[2:3]
	v_mul_f32_e32 v161, v136, v136
	v_fmac_f32_e32 v161, v137, v137
	v_fmac_f32_e32 v161, v138, v138
	v_fmac_f32_e32 v161, v139, v139
	v_fmac_f32_e32 v161, v140, v140
	v_fmac_f32_e32 v161, v141, v141
	v_fmac_f32_e32 v161, v142, v142
	v_fmac_f32_e32 v161, v143, v143
	v_cvt_pk_bf16_f32 v188, v136, v137
	v_cvt_pk_bf16_f32 v189, v138, v139
	v_cvt_pk_bf16_f32 v190, v140, v141
	v_cvt_pk_bf16_f32 v191, v142, v143
	s_add_u32 s2, s24, 0x3a0000
	s_addc_u32 s3, s25, 0
	global_store_dwordx4 v19, v[188:191], s[2:3]
	v_mul_f32_e32 v162, v144, v144
	v_fmac_f32_e32 v162, v145, v145
	v_fmac_f32_e32 v162, v146, v146
	v_fmac_f32_e32 v162, v147, v147
	v_fmac_f32_e32 v162, v148, v148
	v_fmac_f32_e32 v162, v149, v149
	v_fmac_f32_e32 v162, v150, v150
	v_fmac_f32_e32 v162, v151, v151
	v_cvt_pk_bf16_f32 v192, v144, v145
	v_cvt_pk_bf16_f32 v193, v146, v147
	v_cvt_pk_bf16_f32 v194, v148, v149
	v_cvt_pk_bf16_f32 v195, v150, v151
	s_add_u32 s2, s24, 0x3c0000
	s_addc_u32 s3, s25, 0
	global_store_dwordx4 v19, v[192:195], s[2:3]
	v_mul_f32_e32 v163, v152, v152
	v_fmac_f32_e32 v163, v153, v153
	v_fmac_f32_e32 v163, v154, v154
	v_fmac_f32_e32 v163, v155, v155
	v_fmac_f32_e32 v163, v156, v156
	v_fmac_f32_e32 v163, v157, v157
	v_fmac_f32_e32 v163, v158, v158
	v_fmac_f32_e32 v163, v159, v159
	v_cvt_pk_bf16_f32 v196, v152, v153
	v_cvt_pk_bf16_f32 v197, v154, v155
	v_cvt_pk_bf16_f32 v198, v156, v157
	v_cvt_pk_bf16_f32 v199, v158, v159
	s_add_u32 s2, s24, 0x3e0000
	s_addc_u32 s3, s25, 0
	global_store_dwordx4 v19, v[196:199], s[2:3]
	ds_bpermute_b32 v168, v23, v160
	ds_bpermute_b32 v169, v23, v161
	ds_bpermute_b32 v170, v23, v162
	ds_bpermute_b32 v171, v23, v163
	s_waitcnt lgkmcnt(0)
	v_add_f32_e32 v160, v160, v168
	v_add_f32_e32 v161, v161, v169
	v_add_f32_e32 v162, v162, v170
	v_add_f32_e32 v163, v163, v171
	ds_bpermute_b32 v168, v24, v160
	ds_bpermute_b32 v169, v24, v161
	ds_bpermute_b32 v170, v24, v162
	ds_bpermute_b32 v171, v24, v163
	s_waitcnt lgkmcnt(0)
	v_add_f32_e32 v160, v160, v168
	v_add_f32_e32 v161, v161, v169
	v_add_f32_e32 v162, v162, v170
	v_add_f32_e32 v163, v163, v171
	s_mov_b64 exec, 0xffff
	ds_write_b32 v25, v160
	ds_write_b32 v25, v161 offset:64
	ds_write_b32 v25, v162 offset:128
	ds_write_b32 v25, v163 offset:192
	s_mov_b64 exec, -1
	s_waitcnt lgkmcnt(0)
	s_waitcnt vmcnt(16)
	s_barrier
	s_cmp_lg_u32 s92, 0
	s_cbranch_scc1 .Lfftb_nored7
	ds_read_b32 v168, v26
	ds_read_b32 v169, v26 offset:256
	ds_read_b32 v170, v26 offset:512
	ds_read_b32 v171, v26 offset:768
	ds_read_b32 v172, v26 offset:1024
	ds_read_b32 v173, v26 offset:1280
	ds_read_b32 v174, v26 offset:1536
	ds_read_b32 v175, v26 offset:1792
	s_waitcnt lgkmcnt(0)
	v_add_f32_e32 v168, v168, v169
	v_add_f32_e32 v170, v170, v171
	v_add_f32_e32 v172, v172, v173
	v_add_f32_e32 v174, v174, v175
	v_add_f32_e32 v168, v168, v170
	v_add_f32_e32 v172, v172, v174
	v_add_f32_e32 v168, v168, v172
	s_add_u32 s2, s28, 0x38000
	s_addc_u32 s3, s29, 0
	global_atomic_add_f32 v27, v168, s[2:3]
.Lfftb_nored7:
	ds_read_b128 v[32:35], v18
	ds_read_b128 v[36:39], v18 offset:1024
	ds_read_b128 v[40:43], v18 offset:2048
	ds_read_b128 v[44:47], v18 offset:3072
	ds_read_b128 v[48:51], v18 offset:4096
	ds_read_b128 v[52:55], v18 offset:5120
	ds_read_b128 v[56:59], v18 offset:6144
	ds_read_b128 v[60:63], v18 offset:7168
	ds_read_b128 v[64:67], v18 offset:8192
	ds_read_b128 v[68:71], v18 offset:9216
	ds_read_b128 v[72:75], v18 offset:10240
	ds_read_b128 v[76:79], v18 offset:11264
	ds_read_b128 v[80:83], v18 offset:12288
	ds_read_b128 v[84:87], v18 offset:13312
	ds_read_b128 v[88:91], v18 offset:14336
	ds_read_b128 v[92:95], v18 offset:15360
	ds_read_b128 v[96:99], v15
	ds_read_b128 v[100:103], v15 offset:1024
	ds_read_b128 v[104:107], v15 offset:2048
	ds_read_b128 v[108:111], v15 offset:3072
	s_waitcnt lgkmcnt(0)
	s_setprio 1
	v_mfma_f32_16x16x32_bf16 v[128:131], v[96:99], v[32:35], 0
	v_mfma_f32_16x16x32_bf16 v[132:135], v[104:107], v[32:35], 0
	v_mfma_f32_16x16x32_bf16 v[136:139], v[96:99], v[40:43], 0
	v_mfma_f32_16x16x32_bf16 v[140:143], v[104:107], v[40:43], 0
	v_mfma_f32_16x16x32_bf16 v[144:147], v[96:99], v[48:51], 0
	v_mfma_f32_16x16x32_bf16 v[148:151], v[104:107], v[48:51], 0
	v_mfma_f32_16x16x32_bf16 v[152:155], v[96:99], v[56:59], 0
	v_mfma_f32_16x16x32_bf16 v[156:159], v[104:107], v[56:59], 0
	v_mfma_f32_16x16x32_bf16 v[128:131], v[100:103], v[36:39], v[128:131]
	v_mfma_f32_16x16x32_bf16 v[132:135], v[108:111], v[36:39], v[132:135]
	v_mfma_f32_16x16x32_bf16 v[136:139], v[100:103], v[44:47], v[136:139]
	v_mfma_f32_16x16x32_bf16 v[140:143], v[108:111], v[44:47], v[140:143]
	v_mfma_f32_16x16x32_bf16 v[144:147], v[100:103], v[52:55], v[144:147]
	v_mfma_f32_16x16x32_bf16 v[148:151], v[108:111], v[52:55], v[148:151]
	v_mfma_f32_16x16x32_bf16 v[152:155], v[100:103], v[60:63], v[152:155]
	v_mfma_f32_16x16x32_bf16 v[156:159], v[108:111], v[60:63], v[156:159]
	s_setprio 0
	s_add_u32 s0, s22, 0x1000080
	s_addc_u32 s1, s23, 0
	s_add_i32 m0, s38, 0x18000
	s_nop 0
	global_load_lds_dwordx4 v10, s[0:1]
	s_add_i32 m0, s38, 0x18400
	s_nop 0
	global_load_lds_dwordx4 v11, s[0:1]
	s_add_i32 m0, s38, 0x18800
	s_nop 0
	global_load_lds_dwordx4 v12, s[0:1]
	s_add_i32 m0, s38, 0x18c00
	s_nop 0
	global_load_lds_dwordx4 v13, s[0:1]
	s_waitcnt vmcnt(12)
	s_barrier
	ds_read_b128 v[96:99], v16
	ds_read_b128 v[100:103], v16 offset:1024
	ds_read_b128 v[104:107], v16 offset:2048
	ds_read_b128 v[108:111], v16 offset:3072
	s_waitcnt lgkmcnt(0)
	s_setprio 1
	v_mfma_f32_16x16x32_bf16 v[128:131], v[96:99], v[64:67], v[128:131]
	v_mfma_f32_16x16x32_bf16 v[132:135], v[104:107], v[64:67], v[132:135]
	v_mfma_f32_16x16x32_bf16 v[136:139], v[96:99], v[72:75], v[136:139]
	v_mfma_f32_16x16x32_bf16 v[140:143], v[104:107], v[72:75], v[140:143]
	v_mfma_f32_16x16x32_bf16 v[144:147], v[96:99], v[80:83], v[144:147]
	v_mfma_f32_16x16x32_bf16 v[148:151], v[104:107], v[80:83], v[148:151]
	v_mfma_f32_16x16x32_bf16 v[152:155], v[96:99], v[88:91], v[152:155]
	v_mfma_f32_16x16x32_bf16 v[156:159], v[104:107], v[88:91], v[156:159]
	v_mfma_f32_16x16x32_bf16 v[128:131], v[100:103], v[68:71], v[128:131]
	v_mfma_f32_16x16x32_bf16 v[132:135], v[108:111], v[68:71], v[132:135]
	v_mfma_f32_16x16x32_bf16 v[136:139], v[100:103], v[76:79], v[136:139]
	v_mfma_f32_16x16x32_bf16 v[140:143], v[108:111], v[76:79], v[140:143]
	v_mfma_f32_16x16x32_bf16 v[144:147], v[100:103], v[84:87], v[144:147]
	v_mfma_f32_16x16x32_bf16 v[148:151], v[108:111], v[84:87], v[148:151]
	v_mfma_f32_16x16x32_bf16 v[152:155], v[100:103], v[92:95], v[152:155]
	v_mfma_f32_16x16x32_bf16 v[156:159], v[108:111], v[92:95], v[156:159]
	s_setprio 0
	s_nop 7
	v_mul_f32_e32 v160, v128, v128
	v_fmac_f32_e32 v160, v129, v129
	v_fmac_f32_e32 v160, v130, v130
	v_fmac_f32_e32 v160, v131, v131
	v_fmac_f32_e32 v160, v132, v132
	v_fmac_f32_e32 v160, v133, v133
	v_fmac_f32_e32 v160, v134, v134
	v_fmac_f32_e32 v160, v135, v135
	v_cvt_pk_bf16_f32 v184, v128, v129
	v_cvt_pk_bf16_f32 v185, v130, v131
	v_cvt_pk_bf16_f32 v186, v132, v133
	v_cvt_pk_bf16_f32 v187, v134, v135
	s_add_u32 s2, s26, 0x0
	s_addc_u32 s3, s27, 0
	global_store_dwordx4 v20, v[184:187], s[2:3]
	v_mul_f32_e32 v161, v136, v136
	v_fmac_f32_e32 v161, v137, v137
	v_fmac_f32_e32 v161, v138, v138
	v_fmac_f32_e32 v161, v139, v139
	v_fmac_f32_e32 v161, v140, v140
	v_fmac_f32_e32 v161, v141, v141
	v_fmac_f32_e32 v161, v142, v142
	v_fmac_f32_e32 v161, v143, v143
	v_cvt_pk_bf16_f32 v188, v136, v137
	v_cvt_pk_bf16_f32 v189, v138, v139
	v_cvt_pk_bf16_f32 v190, v140, v141
	v_cvt_pk_bf16_f32 v191, v142, v143
	s_add_u32 s2, s26, 0x10000
	s_addc_u32 s3, s27, 0
	global_store_dwordx4 v20, v[188:191], s[2:3]
	v_mul_f32_e32 v162, v144, v144
	v_fmac_f32_e32 v162, v145, v145
	v_fmac_f32_e32 v162, v146, v146
	v_fmac_f32_e32 v162, v147, v147
	v_fmac_f32_e32 v162, v148, v148
	v_fmac_f32_e32 v162, v149, v149
	v_fmac_f32_e32 v162, v150, v150
	v_fmac_f32_e32 v162, v151, v151
	v_cvt_pk_bf16_f32 v192, v144, v145
	v_cvt_pk_bf16_f32 v193, v146, v147
	v_cvt_pk_bf16_f32 v194, v148, v149
	v_cvt_pk_bf16_f32 v195, v150, v151
	s_add_u32 s2, s26, 0x20000
	s_addc_u32 s3, s27, 0
	global_store_dwordx4 v20, v[192:195], s[2:3]
	v_mul_f32_e32 v163, v152, v152
	v_fmac_f32_e32 v163, v153, v153
	v_fmac_f32_e32 v163, v154, v154
	v_fmac_f32_e32 v163, v155, v155
	v_fmac_f32_e32 v163, v156, v156
	v_fmac_f32_e32 v163, v157, v157
	v_fmac_f32_e32 v163, v158, v158
	v_fmac_f32_e32 v163, v159, v159
	v_cvt_pk_bf16_f32 v196, v152, v153
	v_cvt_pk_bf16_f32 v197, v154, v155
	v_cvt_pk_bf16_f32 v198, v156, v157
	v_cvt_pk_bf16_f32 v199, v158, v159
	s_add_u32 s2, s26, 0x30000
	s_addc_u32 s3, s27, 0
	global_store_dwordx4 v20, v[196:199], s[2:3]
	ds_bpermute_b32 v168, v23, v160
	ds_bpermute_b32 v169, v23, v161
	ds_bpermute_b32 v170, v23, v162
	ds_bpermute_b32 v171, v23, v163
	s_waitcnt lgkmcnt(0)
	v_add_f32_e32 v160, v160, v168
	v_add_f32_e32 v161, v161, v169
	v_add_f32_e32 v162, v162, v170
	v_add_f32_e32 v163, v163, v171
	ds_bpermute_b32 v168, v24, v160
	ds_bpermute_b32 v169, v24, v161
	ds_bpermute_b32 v170, v24, v162
	ds_bpermute_b32 v171, v24, v163
	s_waitcnt lgkmcnt(0)
	v_add_f32_e32 v160, v160, v168
	v_add_f32_e32 v161, v161, v169
	v_add_f32_e32 v162, v162, v170
	v_add_f32_e32 v163, v163, v171
	s_mov_b64 exec, 0xffff
	ds_write_b32 v25, v160
	ds_write_b32 v25, v161 offset:64
	ds_write_b32 v25, v162 offset:128
	ds_write_b32 v25, v163 offset:192
	s_mov_b64 exec, -1
	s_waitcnt lgkmcnt(0)
	s_waitcnt vmcnt(12)
	s_barrier
	s_cmp_lg_u32 s92, 0
	s_cbranch_scc1 .Lfftb_nored8
	ds_read_b32 v168, v26
	ds_read_b32 v169, v26 offset:256
	ds_read_b32 v170, v26 offset:512
	ds_read_b32 v171, v26 offset:768
	ds_read_b32 v172, v26 offset:1024
	ds_read_b32 v173, v26 offset:1280
	ds_read_b32 v174, v26 offset:1536
	ds_read_b32 v175, v26 offset:1792
	s_waitcnt lgkmcnt(0)
	v_add_f32_e32 v168, v168, v169
	v_add_f32_e32 v170, v170, v171
	v_add_f32_e32 v172, v172, v173
	v_add_f32_e32 v174, v174, v175
	v_add_f32_e32 v168, v168, v170
	v_add_f32_e32 v172, v172, v174
	v_add_f32_e32 v168, v168, v172
	s_add_u32 s2, s30, 0x0
	s_addc_u32 s3, s31, 0
	global_atomic_add_f32 v28, v168, s[2:3]
.Lfftb_nored8:
	ds_read_b128 v[96:99], v17
	ds_read_b128 v[100:103], v17 offset:1024
	ds_read_b128 v[104:107], v17 offset:2048
	ds_read_b128 v[108:111], v17 offset:3072
	s_waitcnt lgkmcnt(0)
	s_setprio 1
	v_mfma_f32_16x16x32_bf16 v[128:131], v[96:99], v[32:35], 0
	v_mfma_f32_16x16x32_bf16 v[132:135], v[104:107], v[32:35], 0
	v_mfma_f32_16x16x32_bf16 v[136:139], v[96:99], v[40:43], 0
	v_mfma_f32_16x16x32_bf16 v[140:143], v[104:107], v[40:43], 0
	v_mfma_f32_16x16x32_bf16 v[144:147], v[96:99], v[48:51], 0
	v_mfma_f32_16x16x32_bf16 v[148:151], v[104:107], v[48:51], 0
	v_mfma_f32_16x16x32_bf16 v[152:155], v[96:99], v[56:59], 0
	v_mfma_f32_16x16x32_bf16 v[156:159], v[104:107], v[56:59], 0
	v_mfma_f32_16x16x32_bf16 v[128:131], v[100:103], v[36:39], v[128:131]
	v_mfma_f32_16x16x32_bf16 v[132:135], v[108:111], v[36:39], v[132:135]
	v_mfma_f32_16x16x32_bf16 v[136:139], v[100:103], v[44:47], v[136:139]
	v_mfma_f32_16x16x32_bf16 v[140:143], v[108:111], v[44:47], v[140:143]
	v_mfma_f32_16x16x32_bf16 v[144:147], v[100:103], v[52:55], v[144:147]
	v_mfma_f32_16x16x32_bf16 v[148:151], v[108:111], v[52:55], v[148:151]
	v_mfma_f32_16x16x32_bf16 v[152:155], v[100:103], v[60:63], v[152:155]
	v_mfma_f32_16x16x32_bf16 v[156:159], v[108:111], v[60:63], v[156:159]
	s_setprio 0
	s_waitcnt vmcnt(4)
	s_barrier
	ds_read_b128 v[96:99], v29
	ds_read_b128 v[100:103], v29 offset:1024
	ds_read_b128 v[104:107], v29 offset:2048
	ds_read_b128 v[108:111], v29 offset:3072
	s_waitcnt lgkmcnt(0)
	s_setprio 1
	v_mfma_f32_16x16x32_bf16 v[128:131], v[96:99], v[64:67], v[128:131]
	v_mfma_f32_16x16x32_bf16 v[132:135], v[104:107], v[64:67], v[132:135]
	v_mfma_f32_16x16x32_bf16 v[136:139], v[96:99], v[72:75], v[136:139]
	v_mfma_f32_16x16x32_bf16 v[140:143], v[104:107], v[72:75], v[140:143]
	v_mfma_f32_16x16x32_bf16 v[144:147], v[96:99], v[80:83], v[144:147]
	v_mfma_f32_16x16x32_bf16 v[148:151], v[104:107], v[80:83], v[148:151]
	v_mfma_f32_16x16x32_bf16 v[152:155], v[96:99], v[88:91], v[152:155]
	v_mfma_f32_16x16x32_bf16 v[156:159], v[104:107], v[88:91], v[156:159]
	v_mfma_f32_16x16x32_bf16 v[128:131], v[100:103], v[68:71], v[128:131]
	v_mfma_f32_16x16x32_bf16 v[132:135], v[108:111], v[68:71], v[132:135]
	v_mfma_f32_16x16x32_bf16 v[136:139], v[100:103], v[76:79], v[136:139]
	v_mfma_f32_16x16x32_bf16 v[140:143], v[108:111], v[76:79], v[140:143]
	v_mfma_f32_16x16x32_bf16 v[144:147], v[100:103], v[84:87], v[144:147]
	v_mfma_f32_16x16x32_bf16 v[148:151], v[108:111], v[84:87], v[148:151]
	v_mfma_f32_16x16x32_bf16 v[152:155], v[100:103], v[92:95], v[152:155]
	v_mfma_f32_16x16x32_bf16 v[156:159], v[108:111], v[92:95], v[156:159]
	s_setprio 0
	s_nop 7
	v_mul_f32_e32 v160, v128, v128
	v_fmac_f32_e32 v160, v129, v129
	v_fmac_f32_e32 v160, v130, v130
	v_fmac_f32_e32 v160, v131, v131
	v_fmac_f32_e32 v160, v132, v132
	v_fmac_f32_e32 v160, v133, v133
	v_fmac_f32_e32 v160, v134, v134
	v_fmac_f32_e32 v160, v135, v135
	v_cvt_pk_bf16_f32 v184, v128, v129
	v_cvt_pk_bf16_f32 v185, v130, v131
	v_cvt_pk_bf16_f32 v186, v132, v133
	v_cvt_pk_bf16_f32 v187, v134, v135
	s_add_u32 s2, s26, 0x80000
	s_addc_u32 s3, s27, 0
	global_store_dwordx4 v20, v[184:187], s[2:3]
	v_mul_f32_e32 v161, v136, v136
	v_fmac_f32_e32 v161, v137, v137
	v_fmac_f32_e32 v161, v138, v138
	v_fmac_f32_e32 v161, v139, v139
	v_fmac_f32_e32 v161, v140, v140
	v_fmac_f32_e32 v161, v141, v141
	v_fmac_f32_e32 v161, v142, v142
	v_fmac_f32_e32 v161, v143, v143
	v_cvt_pk_bf16_f32 v188, v136, v137
	v_cvt_pk_bf16_f32 v189, v138, v139
	v_cvt_pk_bf16_f32 v190, v140, v141
	v_cvt_pk_bf16_f32 v191, v142, v143
	s_add_u32 s2, s26, 0x90000
	s_addc_u32 s3, s27, 0
	global_store_dwordx4 v20, v[188:191], s[2:3]
	v_mul_f32_e32 v162, v144, v144
	v_fmac_f32_e32 v162, v145, v145
	v_fmac_f32_e32 v162, v146, v146
	v_fmac_f32_e32 v162, v147, v147
	v_fmac_f32_e32 v162, v148, v148
	v_fmac_f32_e32 v162, v149, v149
	v_fmac_f32_e32 v162, v150, v150
	v_fmac_f32_e32 v162, v151, v151
	v_cvt_pk_bf16_f32 v192, v144, v145
	v_cvt_pk_bf16_f32 v193, v146, v147
	v_cvt_pk_bf16_f32 v194, v148, v149
	v_cvt_pk_bf16_f32 v195, v150, v151
	s_add_u32 s2, s26, 0xa0000
	s_addc_u32 s3, s27, 0
	global_store_dwordx4 v20, v[192:195], s[2:3]
	v_mul_f32_e32 v163, v152, v152
	v_fmac_f32_e32 v163, v153, v153
	v_fmac_f32_e32 v163, v154, v154
	v_fmac_f32_e32 v163, v155, v155
	v_fmac_f32_e32 v163, v156, v156
	v_fmac_f32_e32 v163, v157, v157
	v_fmac_f32_e32 v163, v158, v158
	v_fmac_f32_e32 v163, v159, v159
	v_cvt_pk_bf16_f32 v196, v152, v153
	v_cvt_pk_bf16_f32 v197, v154, v155
	v_cvt_pk_bf16_f32 v198, v156, v157
	v_cvt_pk_bf16_f32 v199, v158, v159
	s_add_u32 s2, s26, 0xb0000
	s_addc_u32 s3, s27, 0
	global_store_dwordx4 v20, v[196:199], s[2:3]
	ds_bpermute_b32 v168, v23, v160
	ds_bpermute_b32 v169, v23, v161
	ds_bpermute_b32 v170, v23, v162
	ds_bpermute_b32 v171, v23, v163
	s_waitcnt lgkmcnt(0)
	v_add_f32_e32 v160, v160, v168
	v_add_f32_e32 v161, v161, v169
	v_add_f32_e32 v162, v162, v170
	v_add_f32_e32 v163, v163, v171
	ds_bpermute_b32 v168, v24, v160
	ds_bpermute_b32 v169, v24, v161
	ds_bpermute_b32 v170, v24, v162
	ds_bpermute_b32 v171, v24, v163
	s_waitcnt lgkmcnt(0)
	v_add_f32_e32 v160, v160, v168
	v_add_f32_e32 v161, v161, v169
	v_add_f32_e32 v162, v162, v170
	v_add_f32_e32 v163, v163, v171
	s_mov_b64 exec, 0xffff
	ds_write_b32 v25, v160
	ds_write_b32 v25, v161 offset:64
	ds_write_b32 v25, v162 offset:128
	ds_write_b32 v25, v163 offset:192
	s_mov_b64 exec, -1
	s_waitcnt lgkmcnt(0)
	s_waitcnt vmcnt(0) lgkmcnt(0)
	s_barrier
	s_cmp_lg_u32 s92, 0
	s_cbranch_scc1 .Lfftb_nored9
	ds_read_b32 v168, v26
	ds_read_b32 v169, v26 offset:256
	ds_read_b32 v170, v26 offset:512
	ds_read_b32 v171, v26 offset:768
	ds_read_b32 v172, v26 offset:1024
	ds_read_b32 v173, v26 offset:1280
	ds_read_b32 v174, v26 offset:1536
	ds_read_b32 v175, v26 offset:1792
	s_waitcnt lgkmcnt(0)
	v_add_f32_e32 v168, v168, v169
	v_add_f32_e32 v170, v170, v171
	v_add_f32_e32 v172, v172, v173
	v_add_f32_e32 v174, v174, v175
	v_add_f32_e32 v168, v168, v170
	v_add_f32_e32 v172, v172, v174
	v_add_f32_e32 v168, v168, v172
	s_add_u32 s2, s30, 0x8000
	s_addc_u32 s3, s31, 0
	global_atomic_add_f32 v28, v168, s[2:3]
.Lfftb_nored9:
	s_waitcnt vmcnt(0)
	s_mul_i32 s97, s92, 0x1d1
	v_and_b32_e32 v137, 15, v164
	s_branch .LBB0_665
